# P5 GT/MACC per-thread scratch stores as plain L2 write-back stores (read-back loads keep sc1 L1 bypass) instead of write-through sc1
# speedup vs baseline: 1.0124x; 1.0124x over previous
; __device__ __forceinline__ unsigned cvt_pk_bf16(float lo, float hi) { unsigned r; asm("v_cvt_pk_bf16_f32 %0, %1, %2" : "=v"(r) : "v"(lo), "v"(hi)); return r; }
; __device__ __forceinline__ float lo_bf(unsigned u) { return __uint_as_float(u << 16); }
; __device__ __forceinline__ float hi_bf(unsigned u) { return __uint_as_float(u & 0xffff0000u); }
;     __device__ __forceinline__ void operator()(f32x4 (&acc)[2][2][4][2], const GUnit& u, int wr, int wc, int fr, int fq, int tid) const {
;     ...
;         } else {
;             bf16_t* mp = (bf16_t*)MACC + (size_t)tid * 8;
;             bf16_t* op = O + (size_t)(u.pm * BM + wr * 64 + fr) * DM + u.pn * BM + wc * 32 + 8 * fq;
; #pragma unroll
;             for (int ai = 0; ai < 2; ++ai)
; #pragma unroll
;                 for (int bj = 0; bj < 2; ++bj)
; #pragma unroll
;                     for (int m = 0; m < 4; ++m) {
;                         const u32x4 g = ld_coh16(gp);
;                         u32x4 q = {0u, 0u, 0u, 0u}; if (sub != 1) q = ld_coh16(mp);
;                         f32x4 g0 = {lo_bf(g.x), hi_bf(g.x), lo_bf(g.y), hi_bf(g.y)}, g1 = {lo_bf(g.z), hi_bf(g.z), lo_bf(g.w), hi_bf(g.w)};
;                         f32x4 v0 = g0 * acc[ai][bj][m][0], v1 = g1 * acc[ai][bj][m][1];
;                         if (sub != 1) { v0 += (f32x4){lo_bf(q.x), hi_bf(q.x), lo_bf(q.y), hi_bf(q.y)}; v1 += (f32x4){lo_bf(q.z), hi_bf(q.z), lo_bf(q.w), hi_bf(q.w)}; }
;                         if (sub != 5) { u32x4 w; w.x = cvt_pk_bf16(v0[0], v0[1]); w.y = cvt_pk_bf16(v0[2], v0[3]); w.z = cvt_pk_bf16(v1[0], v1[1]); w.w = cvt_pk_bf16(v1[2], v1[3]); st_coh16(mp, w); }
;                         else { u32x4 w; w.x = cvt_pk_bf16(v0[0], v0[1]); w.y = cvt_pk_bf16(v0[2], v0[3]); w.z = cvt_pk_bf16(v1[0], v1[1]); w.w = cvt_pk_bf16(v1[2], v1[3]);
;                             *(u32x4*)(op + (size_t)(ai * HALF + m * 16) * DM + bj * HALF) = w; }
;                         gp += 4096; mp += 4096; asm volatile("" : "+v"(gp), "+v"(mp) :: "memory"); }
.LBB0_577:
	v_mov_b32_e32 v128, v181
	v_mov_b32_e32 v136, v177
	v_mov_b32_e32 v143, v252
	s_bitcmp1_b32 s96, 0
	s_cselect_b64 s[14:15], -1, 0
	v_ashrrev_i32_e32 v129, 31, v128
	v_lshl_add_u64 v[150:151], v[128:129], 4, s[22:23]
	s_mov_b64 s[12:13], -1
	s_and_b64 vcc, exec, s[14:15]
	v_mov_b64_e32 v[250:251], v[182:183]
	s_cbranch_vccz .LBB0_679
	v_readlane_b32 s12, v255, 36
	v_readlane_b32 s13, v255, 37
	v_readlane_b32 s54, v255, 19
	v_readlane_b32 s55, v255, 20
	v_lshlrev_b32_e32 v129, 4, v128
	s_lshl_b32 s36, s90, 8
	v_readlane_b32 s39, v255, 38
	v_lshlrev_b32_e32 v130, 4, v128
	s_nop 1
	s_add_i32 s36, s36, s39
	v_add_u32_e32 v131, s36, v143
	v_lshlrev_b32_e32 v131, 12, v131
	s_lshl_b32 s36, s97, 9
	s_lshl_b32 s39, s20, 1
	s_add_i32 s36, s36, s39
	v_lshl_add_u32 v138, v136, 4, s36
	v_add_u32_e32 v131, v131, v138
	s_cmp_eq_u32 s96, 1
	s_cbranch_scc1 .Lbe_sub1
	s_cmp_eq_u32 s96, 5
	s_cbranch_scc1 .Lbe_sub5
	global_load_dwordx4 v[188:191], v129, s[22:23] sc1
	global_load_dwordx4 v[192:195], v129, s[12:13] sc1
	v_add_u32_e32 v129, 0x2000, v129
	global_load_dwordx4 v[196:199], v129, s[22:23] sc1
	global_load_dwordx4 v[200:203], v129, s[12:13] sc1
	v_add_u32_e32 v129, 0x2000, v129
	global_load_dwordx4 v[204:207], v129, s[22:23] sc1
	global_load_dwordx4 v[208:211], v129, s[12:13] sc1
	v_add_u32_e32 v129, 0x2000, v129
	global_load_dwordx4 v[212:215], v129, s[22:23] sc1
	global_load_dwordx4 v[216:219], v129, s[12:13] sc1
	v_add_u32_e32 v129, 0x2000, v129
	global_load_dwordx4 v[220:223], v129, s[22:23] sc1
	global_load_dwordx4 v[224:227], v129, s[12:13] sc1
	v_add_u32_e32 v129, 0x2000, v129
	global_load_dwordx4 v[228:231], v129, s[22:23] sc1
	global_load_dwordx4 v[232:235], v129, s[12:13] sc1
	v_add_u32_e32 v129, 0x2000, v129
	global_load_dwordx4 v[236:239], v129, s[22:23] sc1
	global_load_dwordx4 v[240:243], v129, s[12:13] sc1
	v_add_u32_e32 v129, 0x2000, v129
	s_waitcnt vmcnt(12)
	v_lshlrev_b32_e32 v152, 16, v188
	v_and_b32_e32 v153, 0xffff0000, v188
	v_lshlrev_b32_e32 v154, 16, v189
	v_and_b32_e32 v155, 0xffff0000, v189
	v_lshlrev_b32_e32 v156, 16, v190
	v_and_b32_e32 v157, 0xffff0000, v190
	v_lshlrev_b32_e32 v158, 16, v191
	v_and_b32_e32 v159, 0xffff0000, v191
	v_pk_mul_f32 v[124:125], v[124:125], v[152:153]
	v_pk_mul_f32 v[126:127], v[126:127], v[154:155]
	v_pk_mul_f32 v[120:121], v[120:121], v[156:157]
	v_pk_mul_f32 v[122:123], v[122:123], v[158:159]
	v_lshlrev_b32_e32 v152, 16, v192
	v_and_b32_e32 v153, 0xffff0000, v192
	v_lshlrev_b32_e32 v154, 16, v193
	v_and_b32_e32 v155, 0xffff0000, v193
	v_lshlrev_b32_e32 v156, 16, v194
	v_and_b32_e32 v157, 0xffff0000, v194
	v_lshlrev_b32_e32 v158, 16, v195
	v_and_b32_e32 v159, 0xffff0000, v195
	v_pk_add_f32 v[124:125], v[124:125], v[152:153]
	v_pk_add_f32 v[126:127], v[126:127], v[154:155]
	v_pk_add_f32 v[120:121], v[120:121], v[156:157]
	v_pk_add_f32 v[122:123], v[122:123], v[158:159]
	v_cvt_pk_bf16_f32 v132, v124, v125
	v_cvt_pk_bf16_f32 v133, v126, v127
	v_cvt_pk_bf16_f32 v134, v120, v121
	v_cvt_pk_bf16_f32 v135, v122, v123
	global_store_dwordx4 v130, v[132:135], s[12:13]
	v_add_u32_e32 v130, 0x2000, v130
	global_load_dwordx4 v[188:191], v129, s[22:23] sc1
	global_load_dwordx4 v[192:195], v129, s[12:13] sc1
	v_add_u32_e32 v129, 0x2000, v129
	s_waitcnt vmcnt(13)
	v_lshlrev_b32_e32 v152, 16, v196
	v_and_b32_e32 v153, 0xffff0000, v196
	v_lshlrev_b32_e32 v154, 16, v197
	v_and_b32_e32 v155, 0xffff0000, v197
	v_lshlrev_b32_e32 v156, 16, v198
	v_and_b32_e32 v157, 0xffff0000, v198
	v_lshlrev_b32_e32 v158, 16, v199
	v_and_b32_e32 v159, 0xffff0000, v199
	v_pk_mul_f32 v[116:117], v[116:117], v[152:153]
	v_pk_mul_f32 v[118:119], v[118:119], v[154:155]
	v_pk_mul_f32 v[112:113], v[112:113], v[156:157]
	v_pk_mul_f32 v[114:115], v[114:115], v[158:159]
	v_lshlrev_b32_e32 v152, 16, v200
	v_and_b32_e32 v153, 0xffff0000, v200
	v_lshlrev_b32_e32 v154, 16, v201
	v_and_b32_e32 v155, 0xffff0000, v201
	v_lshlrev_b32_e32 v156, 16, v202
	v_and_b32_e32 v157, 0xffff0000, v202
	v_lshlrev_b32_e32 v158, 16, v203
	v_and_b32_e32 v159, 0xffff0000, v203
	v_pk_add_f32 v[116:117], v[116:117], v[152:153]
	v_pk_add_f32 v[118:119], v[118:119], v[154:155]
	v_pk_add_f32 v[112:113], v[112:113], v[156:157]
	v_pk_add_f32 v[114:115], v[114:115], v[158:159]
	v_cvt_pk_bf16_f32 v132, v116, v117
	v_cvt_pk_bf16_f32 v133, v118, v119
	v_cvt_pk_bf16_f32 v134, v112, v113
	v_cvt_pk_bf16_f32 v135, v114, v115
	global_store_dwordx4 v130, v[132:135], s[12:13]
	v_add_u32_e32 v130, 0x2000, v130
	global_load_dwordx4 v[196:199], v129, s[22:23] sc1
	global_load_dwordx4 v[200:203], v129, s[12:13] sc1
	v_add_u32_e32 v129, 0x2000, v129
	s_waitcnt vmcnt(14)
	v_lshlrev_b32_e32 v152, 16, v204
	v_and_b32_e32 v153, 0xffff0000, v204
	v_lshlrev_b32_e32 v154, 16, v205
	v_and_b32_e32 v155, 0xffff0000, v205
	v_lshlrev_b32_e32 v156, 16, v206
	v_and_b32_e32 v157, 0xffff0000, v206
	v_lshlrev_b32_e32 v158, 16, v207
	v_and_b32_e32 v159, 0xffff0000, v207
	v_pk_mul_f32 v[108:109], v[108:109], v[152:153]
	v_pk_mul_f32 v[110:111], v[110:111], v[154:155]
	v_pk_mul_f32 v[104:105], v[104:105], v[156:157]
	v_pk_mul_f32 v[106:107], v[106:107], v[158:159]
	v_lshlrev_b32_e32 v152, 16, v208
	v_and_b32_e32 v153, 0xffff0000, v208
	v_lshlrev_b32_e32 v154, 16, v209
	v_and_b32_e32 v155, 0xffff0000, v209
	v_lshlrev_b32_e32 v156, 16, v210
	v_and_b32_e32 v157, 0xffff0000, v210
	v_lshlrev_b32_e32 v158, 16, v211
	v_and_b32_e32 v159, 0xffff0000, v211
	v_pk_add_f32 v[108:109], v[108:109], v[152:153]
	v_pk_add_f32 v[110:111], v[110:111], v[154:155]
	v_pk_add_f32 v[104:105], v[104:105], v[156:157]
	v_pk_add_f32 v[106:107], v[106:107], v[158:159]
	v_cvt_pk_bf16_f32 v132, v108, v109
	v_cvt_pk_bf16_f32 v133, v110, v111
	v_cvt_pk_bf16_f32 v134, v104, v105
	v_cvt_pk_bf16_f32 v135, v106, v107
	global_store_dwordx4 v130, v[132:135], s[12:13]
	v_add_u32_e32 v130, 0x2000, v130
	global_load_dwordx4 v[204:207], v129, s[22:23] sc1
	global_load_dwordx4 v[208:211], v129, s[12:13] sc1
	v_add_u32_e32 v129, 0x2000, v129
	s_waitcnt vmcnt(15)
; __device__ __forceinline__ unsigned cvt_pk_bf16(float lo, float hi) { unsigned r; asm("v_cvt_pk_bf16_f32 %0, %1, %2" : "=v"(r) : "v"(lo), "v"(hi)); return r; }
; __device__ __forceinline__ float lo_bf(unsigned u) { return __uint_as_float(u << 16); }
; __device__ __forceinline__ float hi_bf(unsigned u) { return __uint_as_float(u & 0xffff0000u); }
;     __device__ __forceinline__ void operator()(f32x4 (&acc)[2][2][4][2], const GUnit& u, int wr, int wc, int fr, int fq, int tid) const {
;     ...
;                     for (int m = 0; m < 4; ++m) {
;                         const u32x4 g = ld_coh16(gp);
;                         u32x4 q = {0u, 0u, 0u, 0u}; if (sub != 1) q = ld_coh16(mp);
;                         f32x4 g0 = {lo_bf(g.x), hi_bf(g.x), lo_bf(g.y), hi_bf(g.y)}, g1 = {lo_bf(g.z), hi_bf(g.z), lo_bf(g.w), hi_bf(g.w)};
;                         f32x4 v0 = g0 * acc[ai][bj][m][0], v1 = g1 * acc[ai][bj][m][1];
;                         if (sub != 1) { v0 += (f32x4){lo_bf(q.x), hi_bf(q.x), lo_bf(q.y), hi_bf(q.y)}; v1 += (f32x4){lo_bf(q.z), hi_bf(q.z), lo_bf(q.w), hi_bf(q.w)}; }
;                         if (sub != 5) { u32x4 w; w.x = cvt_pk_bf16(v0[0], v0[1]); w.y = cvt_pk_bf16(v0[2], v0[3]); w.z = cvt_pk_bf16(v1[0], v1[1]); w.w = cvt_pk_bf16(v1[2], v1[3]); st_coh16(mp, w); }
;                         else { u32x4 w; w.x = cvt_pk_bf16(v0[0], v0[1]); w.y = cvt_pk_bf16(v0[2], v0[3]); w.z = cvt_pk_bf16(v1[0], v1[1]); w.w = cvt_pk_bf16(v1[2], v1[3]);
;                             *(u32x4*)(op + (size_t)(ai * HALF + m * 16) * DM + bj * HALF) = w; }
;                         gp += 4096; mp += 4096; asm volatile("" : "+v"(gp), "+v"(mp) :: "memory"); }
	v_lshlrev_b32_e32 v152, 16, v212
	v_and_b32_e32 v153, 0xffff0000, v212
	v_lshlrev_b32_e32 v154, 16, v213
	v_and_b32_e32 v155, 0xffff0000, v213
	v_lshlrev_b32_e32 v156, 16, v214
	v_and_b32_e32 v157, 0xffff0000, v214
	v_lshlrev_b32_e32 v158, 16, v215
	v_and_b32_e32 v159, 0xffff0000, v215
	v_pk_mul_f32 v[100:101], v[100:101], v[152:153]
	v_pk_mul_f32 v[102:103], v[102:103], v[154:155]
	v_pk_mul_f32 v[96:97], v[96:97], v[156:157]
	v_pk_mul_f32 v[98:99], v[98:99], v[158:159]
	v_lshlrev_b32_e32 v152, 16, v216
	v_and_b32_e32 v153, 0xffff0000, v216
	v_lshlrev_b32_e32 v154, 16, v217
	v_and_b32_e32 v155, 0xffff0000, v217
	v_lshlrev_b32_e32 v156, 16, v218
	v_and_b32_e32 v157, 0xffff0000, v218
	v_lshlrev_b32_e32 v158, 16, v219
	v_and_b32_e32 v159, 0xffff0000, v219
	v_pk_add_f32 v[100:101], v[100:101], v[152:153]
	v_pk_add_f32 v[102:103], v[102:103], v[154:155]
	v_pk_add_f32 v[96:97], v[96:97], v[156:157]
	v_pk_add_f32 v[98:99], v[98:99], v[158:159]
	v_cvt_pk_bf16_f32 v132, v100, v101
	v_cvt_pk_bf16_f32 v133, v102, v103
	v_cvt_pk_bf16_f32 v134, v96, v97
	v_cvt_pk_bf16_f32 v135, v98, v99
	global_store_dwordx4 v130, v[132:135], s[12:13]
	v_add_u32_e32 v130, 0x2000, v130
	global_load_dwordx4 v[212:215], v129, s[22:23] sc1
	global_load_dwordx4 v[216:219], v129, s[12:13] sc1
	v_add_u32_e32 v129, 0x2000, v129
	s_waitcnt vmcnt(16)
	v_lshlrev_b32_e32 v152, 16, v220
	v_and_b32_e32 v153, 0xffff0000, v220
	v_lshlrev_b32_e32 v154, 16, v221
	v_and_b32_e32 v155, 0xffff0000, v221
	v_lshlrev_b32_e32 v156, 16, v222
	v_and_b32_e32 v157, 0xffff0000, v222
	v_lshlrev_b32_e32 v158, 16, v223
	v_and_b32_e32 v159, 0xffff0000, v223
	v_pk_mul_f32 v[92:93], v[92:93], v[152:153]
	v_pk_mul_f32 v[94:95], v[94:95], v[154:155]
	v_pk_mul_f32 v[88:89], v[88:89], v[156:157]
	v_pk_mul_f32 v[90:91], v[90:91], v[158:159]
	v_lshlrev_b32_e32 v152, 16, v224
	v_and_b32_e32 v153, 0xffff0000, v224
	v_lshlrev_b32_e32 v154, 16, v225
	v_and_b32_e32 v155, 0xffff0000, v225
	v_lshlrev_b32_e32 v156, 16, v226
	v_and_b32_e32 v157, 0xffff0000, v226
	v_lshlrev_b32_e32 v158, 16, v227
	v_and_b32_e32 v159, 0xffff0000, v227
	v_pk_add_f32 v[92:93], v[92:93], v[152:153]
	v_pk_add_f32 v[94:95], v[94:95], v[154:155]
	v_pk_add_f32 v[88:89], v[88:89], v[156:157]
	v_pk_add_f32 v[90:91], v[90:91], v[158:159]
	v_cvt_pk_bf16_f32 v132, v92, v93
	v_cvt_pk_bf16_f32 v133, v94, v95
	v_cvt_pk_bf16_f32 v134, v88, v89
	v_cvt_pk_bf16_f32 v135, v90, v91
	global_store_dwordx4 v130, v[132:135], s[12:13]
	v_add_u32_e32 v130, 0x2000, v130
	global_load_dwordx4 v[220:223], v129, s[22:23] sc1
	global_load_dwordx4 v[224:227], v129, s[12:13] sc1
	v_add_u32_e32 v129, 0x2000, v129
	s_waitcnt vmcnt(17)
	v_lshlrev_b32_e32 v152, 16, v228
	v_and_b32_e32 v153, 0xffff0000, v228
	v_lshlrev_b32_e32 v154, 16, v229
	v_and_b32_e32 v155, 0xffff0000, v229
	v_lshlrev_b32_e32 v156, 16, v230
	v_and_b32_e32 v157, 0xffff0000, v230
	v_lshlrev_b32_e32 v158, 16, v231
	v_and_b32_e32 v159, 0xffff0000, v231
	v_pk_mul_f32 v[84:85], v[84:85], v[152:153]
	v_pk_mul_f32 v[86:87], v[86:87], v[154:155]
	v_pk_mul_f32 v[80:81], v[80:81], v[156:157]
	v_pk_mul_f32 v[82:83], v[82:83], v[158:159]
	v_lshlrev_b32_e32 v152, 16, v232
	v_and_b32_e32 v153, 0xffff0000, v232
	v_lshlrev_b32_e32 v154, 16, v233
	v_and_b32_e32 v155, 0xffff0000, v233
	v_lshlrev_b32_e32 v156, 16, v234
	v_and_b32_e32 v157, 0xffff0000, v234
	v_lshlrev_b32_e32 v158, 16, v235
	v_and_b32_e32 v159, 0xffff0000, v235
	v_pk_add_f32 v[84:85], v[84:85], v[152:153]
	v_pk_add_f32 v[86:87], v[86:87], v[154:155]
	v_pk_add_f32 v[80:81], v[80:81], v[156:157]
	v_pk_add_f32 v[82:83], v[82:83], v[158:159]
	v_cvt_pk_bf16_f32 v132, v84, v85
	v_cvt_pk_bf16_f32 v133, v86, v87
	v_cvt_pk_bf16_f32 v134, v80, v81
	v_cvt_pk_bf16_f32 v135, v82, v83
	global_store_dwordx4 v130, v[132:135], s[12:13]
	v_add_u32_e32 v130, 0x2000, v130
	global_load_dwordx4 v[228:231], v129, s[22:23] sc1
	global_load_dwordx4 v[232:235], v129, s[12:13] sc1
	v_add_u32_e32 v129, 0x2000, v129
	s_waitcnt vmcnt(18)
	v_lshlrev_b32_e32 v152, 16, v236
	v_and_b32_e32 v153, 0xffff0000, v236
	v_lshlrev_b32_e32 v154, 16, v237
	v_and_b32_e32 v155, 0xffff0000, v237
	v_lshlrev_b32_e32 v156, 16, v238
	v_and_b32_e32 v157, 0xffff0000, v238
	v_lshlrev_b32_e32 v158, 16, v239
	v_and_b32_e32 v159, 0xffff0000, v239
	v_pk_mul_f32 v[76:77], v[76:77], v[152:153]
	v_pk_mul_f32 v[78:79], v[78:79], v[154:155]
	v_pk_mul_f32 v[72:73], v[72:73], v[156:157]
	v_pk_mul_f32 v[74:75], v[74:75], v[158:159]
	v_lshlrev_b32_e32 v152, 16, v240
	v_and_b32_e32 v153, 0xffff0000, v240
	v_lshlrev_b32_e32 v154, 16, v241
	v_and_b32_e32 v155, 0xffff0000, v241
	v_lshlrev_b32_e32 v156, 16, v242
	v_and_b32_e32 v157, 0xffff0000, v242
	v_lshlrev_b32_e32 v158, 16, v243
	v_and_b32_e32 v159, 0xffff0000, v243
	v_pk_add_f32 v[76:77], v[76:77], v[152:153]
	v_pk_add_f32 v[78:79], v[78:79], v[154:155]
	v_pk_add_f32 v[72:73], v[72:73], v[156:157]
	v_pk_add_f32 v[74:75], v[74:75], v[158:159]
	v_cvt_pk_bf16_f32 v132, v76, v77
	v_cvt_pk_bf16_f32 v133, v78, v79
	v_cvt_pk_bf16_f32 v134, v72, v73
	v_cvt_pk_bf16_f32 v135, v74, v75
	global_store_dwordx4 v130, v[132:135], s[12:13]
	v_add_u32_e32 v130, 0x2000, v130
	global_load_dwordx4 v[236:239], v129, s[22:23] sc1
	global_load_dwordx4 v[240:243], v129, s[12:13] sc1
	v_add_u32_e32 v129, 0x2000, v129
	s_waitcnt vmcnt(18)
; __device__ __forceinline__ unsigned cvt_pk_bf16(float lo, float hi) { unsigned r; asm("v_cvt_pk_bf16_f32 %0, %1, %2" : "=v"(r) : "v"(lo), "v"(hi)); return r; }
; __device__ __forceinline__ float lo_bf(unsigned u) { return __uint_as_float(u << 16); }
; __device__ __forceinline__ float hi_bf(unsigned u) { return __uint_as_float(u & 0xffff0000u); }
;     __device__ __forceinline__ void operator()(f32x4 (&acc)[2][2][4][2], const GUnit& u, int wr, int wc, int fr, int fq, int tid) const {
;     ...
;                     for (int m = 0; m < 4; ++m) {
;                         const u32x4 g = ld_coh16(gp);
;                         u32x4 q = {0u, 0u, 0u, 0u}; if (sub != 1) q = ld_coh16(mp);
;                         f32x4 g0 = {lo_bf(g.x), hi_bf(g.x), lo_bf(g.y), hi_bf(g.y)}, g1 = {lo_bf(g.z), hi_bf(g.z), lo_bf(g.w), hi_bf(g.w)};
;                         f32x4 v0 = g0 * acc[ai][bj][m][0], v1 = g1 * acc[ai][bj][m][1];
;                         if (sub != 1) { v0 += (f32x4){lo_bf(q.x), hi_bf(q.x), lo_bf(q.y), hi_bf(q.y)}; v1 += (f32x4){lo_bf(q.z), hi_bf(q.z), lo_bf(q.w), hi_bf(q.w)}; }
;                         if (sub != 5) { u32x4 w; w.x = cvt_pk_bf16(v0[0], v0[1]); w.y = cvt_pk_bf16(v0[2], v0[3]); w.z = cvt_pk_bf16(v1[0], v1[1]); w.w = cvt_pk_bf16(v1[2], v1[3]); st_coh16(mp, w); }
;                         else { u32x4 w; w.x = cvt_pk_bf16(v0[0], v0[1]); w.y = cvt_pk_bf16(v0[2], v0[3]); w.z = cvt_pk_bf16(v1[0], v1[1]); w.w = cvt_pk_bf16(v1[2], v1[3]);
;                             *(u32x4*)(op + (size_t)(ai * HALF + m * 16) * DM + bj * HALF) = w; }
;                         gp += 4096; mp += 4096; asm volatile("" : "+v"(gp), "+v"(mp) :: "memory"); }
	v_lshlrev_b32_e32 v152, 16, v188
	v_and_b32_e32 v153, 0xffff0000, v188
	v_lshlrev_b32_e32 v154, 16, v189
	v_and_b32_e32 v155, 0xffff0000, v189
	v_lshlrev_b32_e32 v156, 16, v190
	v_and_b32_e32 v157, 0xffff0000, v190
	v_lshlrev_b32_e32 v158, 16, v191
	v_and_b32_e32 v159, 0xffff0000, v191
	v_pk_mul_f32 v[68:69], v[68:69], v[152:153]
	v_pk_mul_f32 v[70:71], v[70:71], v[154:155]
	v_pk_mul_f32 v[64:65], v[64:65], v[156:157]
	v_pk_mul_f32 v[66:67], v[66:67], v[158:159]
	v_lshlrev_b32_e32 v152, 16, v192
	v_and_b32_e32 v153, 0xffff0000, v192
	v_lshlrev_b32_e32 v154, 16, v193
	v_and_b32_e32 v155, 0xffff0000, v193
	v_lshlrev_b32_e32 v156, 16, v194
	v_and_b32_e32 v157, 0xffff0000, v194
	v_lshlrev_b32_e32 v158, 16, v195
	v_and_b32_e32 v159, 0xffff0000, v195
	v_pk_add_f32 v[68:69], v[68:69], v[152:153]
	v_pk_add_f32 v[70:71], v[70:71], v[154:155]
	v_pk_add_f32 v[64:65], v[64:65], v[156:157]
	v_pk_add_f32 v[66:67], v[66:67], v[158:159]
	v_cvt_pk_bf16_f32 v132, v68, v69
	v_cvt_pk_bf16_f32 v133, v70, v71
	v_cvt_pk_bf16_f32 v134, v64, v65
	v_cvt_pk_bf16_f32 v135, v66, v67
	global_store_dwordx4 v130, v[132:135], s[12:13]
	v_add_u32_e32 v130, 0x2000, v130
	global_load_dwordx4 v[188:191], v129, s[22:23] sc1
	global_load_dwordx4 v[192:195], v129, s[12:13] sc1
	v_add_u32_e32 v129, 0x2000, v129
	s_waitcnt vmcnt(18)
	v_lshlrev_b32_e32 v152, 16, v196
	v_and_b32_e32 v153, 0xffff0000, v196
	v_lshlrev_b32_e32 v154, 16, v197
	v_and_b32_e32 v155, 0xffff0000, v197
	v_lshlrev_b32_e32 v156, 16, v198
	v_and_b32_e32 v157, 0xffff0000, v198
	v_lshlrev_b32_e32 v158, 16, v199
	v_and_b32_e32 v159, 0xffff0000, v199
	v_pk_mul_f32 v[60:61], v[60:61], v[152:153]
	v_pk_mul_f32 v[62:63], v[62:63], v[154:155]
	v_pk_mul_f32 v[56:57], v[56:57], v[156:157]
	v_pk_mul_f32 v[58:59], v[58:59], v[158:159]
	v_lshlrev_b32_e32 v152, 16, v200
	v_and_b32_e32 v153, 0xffff0000, v200
	v_lshlrev_b32_e32 v154, 16, v201
	v_and_b32_e32 v155, 0xffff0000, v201
	v_lshlrev_b32_e32 v156, 16, v202
	v_and_b32_e32 v157, 0xffff0000, v202
	v_lshlrev_b32_e32 v158, 16, v203
	v_and_b32_e32 v159, 0xffff0000, v203
	v_pk_add_f32 v[60:61], v[60:61], v[152:153]
	v_pk_add_f32 v[62:63], v[62:63], v[154:155]
	v_pk_add_f32 v[56:57], v[56:57], v[156:157]
	v_pk_add_f32 v[58:59], v[58:59], v[158:159]
	v_cvt_pk_bf16_f32 v132, v60, v61
	v_cvt_pk_bf16_f32 v133, v62, v63
	v_cvt_pk_bf16_f32 v134, v56, v57
	v_cvt_pk_bf16_f32 v135, v58, v59
	global_store_dwordx4 v130, v[132:135], s[12:13]
	v_add_u32_e32 v130, 0x2000, v130
	global_load_dwordx4 v[196:199], v129, s[22:23] sc1
	global_load_dwordx4 v[200:203], v129, s[12:13] sc1
	v_add_u32_e32 v129, 0x2000, v129
	s_waitcnt vmcnt(18)
	v_lshlrev_b32_e32 v152, 16, v204
	v_and_b32_e32 v153, 0xffff0000, v204
	v_lshlrev_b32_e32 v154, 16, v205
	v_and_b32_e32 v155, 0xffff0000, v205
	v_lshlrev_b32_e32 v156, 16, v206
	v_and_b32_e32 v157, 0xffff0000, v206
	v_lshlrev_b32_e32 v158, 16, v207
	v_and_b32_e32 v159, 0xffff0000, v207
	v_pk_mul_f32 v[52:53], v[52:53], v[152:153]
	v_pk_mul_f32 v[54:55], v[54:55], v[154:155]
	v_pk_mul_f32 v[48:49], v[48:49], v[156:157]
	v_pk_mul_f32 v[50:51], v[50:51], v[158:159]
	v_lshlrev_b32_e32 v152, 16, v208
	v_and_b32_e32 v153, 0xffff0000, v208
	v_lshlrev_b32_e32 v154, 16, v209
	v_and_b32_e32 v155, 0xffff0000, v209
	v_lshlrev_b32_e32 v156, 16, v210
	v_and_b32_e32 v157, 0xffff0000, v210
	v_lshlrev_b32_e32 v158, 16, v211
	v_and_b32_e32 v159, 0xffff0000, v211
	v_pk_add_f32 v[52:53], v[52:53], v[152:153]
	v_pk_add_f32 v[54:55], v[54:55], v[154:155]
	v_pk_add_f32 v[48:49], v[48:49], v[156:157]
	v_pk_add_f32 v[50:51], v[50:51], v[158:159]
	v_cvt_pk_bf16_f32 v132, v52, v53
	v_cvt_pk_bf16_f32 v133, v54, v55
	v_cvt_pk_bf16_f32 v134, v48, v49
	v_cvt_pk_bf16_f32 v135, v50, v51
	global_store_dwordx4 v130, v[132:135], s[12:13]
	v_add_u32_e32 v130, 0x2000, v130
	s_waitcnt vmcnt(16)
	v_lshlrev_b32_e32 v152, 16, v212
	v_and_b32_e32 v153, 0xffff0000, v212
	v_lshlrev_b32_e32 v154, 16, v213
	v_and_b32_e32 v155, 0xffff0000, v213
	v_lshlrev_b32_e32 v156, 16, v214
	v_and_b32_e32 v157, 0xffff0000, v214
	v_lshlrev_b32_e32 v158, 16, v215
	v_and_b32_e32 v159, 0xffff0000, v215
	v_pk_mul_f32 v[44:45], v[44:45], v[152:153]
	v_pk_mul_f32 v[46:47], v[46:47], v[154:155]
	v_pk_mul_f32 v[40:41], v[40:41], v[156:157]
	v_pk_mul_f32 v[42:43], v[42:43], v[158:159]
	v_lshlrev_b32_e32 v152, 16, v216
	v_and_b32_e32 v153, 0xffff0000, v216
	v_lshlrev_b32_e32 v154, 16, v217
	v_and_b32_e32 v155, 0xffff0000, v217
	v_lshlrev_b32_e32 v156, 16, v218
	v_and_b32_e32 v157, 0xffff0000, v218
	v_lshlrev_b32_e32 v158, 16, v219
	v_and_b32_e32 v159, 0xffff0000, v219
	v_pk_add_f32 v[44:45], v[44:45], v[152:153]
	v_pk_add_f32 v[46:47], v[46:47], v[154:155]
	v_pk_add_f32 v[40:41], v[40:41], v[156:157]
	v_pk_add_f32 v[42:43], v[42:43], v[158:159]
	v_cvt_pk_bf16_f32 v132, v44, v45
	v_cvt_pk_bf16_f32 v133, v46, v47
	v_cvt_pk_bf16_f32 v134, v40, v41
	v_cvt_pk_bf16_f32 v135, v42, v43
	global_store_dwordx4 v130, v[132:135], s[12:13]
	v_add_u32_e32 v130, 0x2000, v130
	s_waitcnt vmcnt(14)
	v_lshlrev_b32_e32 v152, 16, v220
	v_and_b32_e32 v153, 0xffff0000, v220
	v_lshlrev_b32_e32 v154, 16, v221
	v_and_b32_e32 v155, 0xffff0000, v221
	v_lshlrev_b32_e32 v156, 16, v222
	v_and_b32_e32 v157, 0xffff0000, v222
	v_lshlrev_b32_e32 v158, 16, v223
	v_and_b32_e32 v159, 0xffff0000, v223
	v_pk_mul_f32 v[36:37], v[36:37], v[152:153]
	v_pk_mul_f32 v[38:39], v[38:39], v[154:155]
	v_pk_mul_f32 v[32:33], v[32:33], v[156:157]
	v_pk_mul_f32 v[34:35], v[34:35], v[158:159]
	v_lshlrev_b32_e32 v152, 16, v224
	v_and_b32_e32 v153, 0xffff0000, v224
	v_lshlrev_b32_e32 v154, 16, v225
	v_and_b32_e32 v155, 0xffff0000, v225
	v_lshlrev_b32_e32 v156, 16, v226
	v_and_b32_e32 v157, 0xffff0000, v226
	v_lshlrev_b32_e32 v158, 16, v227
	v_and_b32_e32 v159, 0xffff0000, v227
	v_pk_add_f32 v[36:37], v[36:37], v[152:153]
	v_pk_add_f32 v[38:39], v[38:39], v[154:155]
	v_pk_add_f32 v[32:33], v[32:33], v[156:157]
	v_pk_add_f32 v[34:35], v[34:35], v[158:159]
	v_cvt_pk_bf16_f32 v132, v36, v37
	v_cvt_pk_bf16_f32 v133, v38, v39
	v_cvt_pk_bf16_f32 v134, v32, v33
	v_cvt_pk_bf16_f32 v135, v34, v35
	global_store_dwordx4 v130, v[132:135], s[12:13]
	v_add_u32_e32 v130, 0x2000, v130
	s_waitcnt vmcnt(12)
; __device__ __forceinline__ unsigned cvt_pk_bf16(float lo, float hi) { unsigned r; asm("v_cvt_pk_bf16_f32 %0, %1, %2" : "=v"(r) : "v"(lo), "v"(hi)); return r; }
; __device__ __forceinline__ float lo_bf(unsigned u) { return __uint_as_float(u << 16); }
; __device__ __forceinline__ float hi_bf(unsigned u) { return __uint_as_float(u & 0xffff0000u); }
;     __device__ __forceinline__ void operator()(f32x4 (&acc)[2][2][4][2], const GUnit& u, int wr, int wc, int fr, int fq, int tid) const {
;     ...
;                     for (int m = 0; m < 4; ++m) {
;                         const u32x4 g = ld_coh16(gp);
;                         u32x4 q = {0u, 0u, 0u, 0u}; if (sub != 1) q = ld_coh16(mp);
;                         f32x4 g0 = {lo_bf(g.x), hi_bf(g.x), lo_bf(g.y), hi_bf(g.y)}, g1 = {lo_bf(g.z), hi_bf(g.z), lo_bf(g.w), hi_bf(g.w)};
;                         f32x4 v0 = g0 * acc[ai][bj][m][0], v1 = g1 * acc[ai][bj][m][1];
;                         if (sub != 1) { v0 += (f32x4){lo_bf(q.x), hi_bf(q.x), lo_bf(q.y), hi_bf(q.y)}; v1 += (f32x4){lo_bf(q.z), hi_bf(q.z), lo_bf(q.w), hi_bf(q.w)}; }
;                         if (sub != 5) { u32x4 w; w.x = cvt_pk_bf16(v0[0], v0[1]); w.y = cvt_pk_bf16(v0[2], v0[3]); w.z = cvt_pk_bf16(v1[0], v1[1]); w.w = cvt_pk_bf16(v1[2], v1[3]); st_coh16(mp, w); }
;                         else { u32x4 w; w.x = cvt_pk_bf16(v0[0], v0[1]); w.y = cvt_pk_bf16(v0[2], v0[3]); w.z = cvt_pk_bf16(v1[0], v1[1]); w.w = cvt_pk_bf16(v1[2], v1[3]);
;                             *(u32x4*)(op + (size_t)(ai * HALF + m * 16) * DM + bj * HALF) = w; }
;                         gp += 4096; mp += 4096; asm volatile("" : "+v"(gp), "+v"(mp) :: "memory"); }
	v_lshlrev_b32_e32 v152, 16, v228
	v_and_b32_e32 v153, 0xffff0000, v228
	v_lshlrev_b32_e32 v154, 16, v229
	v_and_b32_e32 v155, 0xffff0000, v229
	v_lshlrev_b32_e32 v156, 16, v230
	v_and_b32_e32 v157, 0xffff0000, v230
	v_lshlrev_b32_e32 v158, 16, v231
	v_and_b32_e32 v159, 0xffff0000, v231
	v_pk_mul_f32 v[28:29], v[28:29], v[152:153]
	v_pk_mul_f32 v[30:31], v[30:31], v[154:155]
	v_pk_mul_f32 v[24:25], v[24:25], v[156:157]
	v_pk_mul_f32 v[26:27], v[26:27], v[158:159]
	v_lshlrev_b32_e32 v152, 16, v232
	v_and_b32_e32 v153, 0xffff0000, v232
	v_lshlrev_b32_e32 v154, 16, v233
	v_and_b32_e32 v155, 0xffff0000, v233
	v_lshlrev_b32_e32 v156, 16, v234
	v_and_b32_e32 v157, 0xffff0000, v234
	v_lshlrev_b32_e32 v158, 16, v235
	v_and_b32_e32 v159, 0xffff0000, v235
	v_pk_add_f32 v[28:29], v[28:29], v[152:153]
	v_pk_add_f32 v[30:31], v[30:31], v[154:155]
	v_pk_add_f32 v[24:25], v[24:25], v[156:157]
	v_pk_add_f32 v[26:27], v[26:27], v[158:159]
	v_cvt_pk_bf16_f32 v132, v28, v29
	v_cvt_pk_bf16_f32 v133, v30, v31
	v_cvt_pk_bf16_f32 v134, v24, v25
	v_cvt_pk_bf16_f32 v135, v26, v27
	global_store_dwordx4 v130, v[132:135], s[12:13]
	v_add_u32_e32 v130, 0x2000, v130
	s_waitcnt vmcnt(10)
	v_lshlrev_b32_e32 v152, 16, v236
	v_and_b32_e32 v153, 0xffff0000, v236
	v_lshlrev_b32_e32 v154, 16, v237
	v_and_b32_e32 v155, 0xffff0000, v237
	v_lshlrev_b32_e32 v156, 16, v238
	v_and_b32_e32 v157, 0xffff0000, v238
	v_lshlrev_b32_e32 v158, 16, v239
	v_and_b32_e32 v159, 0xffff0000, v239
	v_pk_mul_f32 v[20:21], v[20:21], v[152:153]
	v_pk_mul_f32 v[22:23], v[22:23], v[154:155]
	v_pk_mul_f32 v[16:17], v[16:17], v[156:157]
	v_pk_mul_f32 v[18:19], v[18:19], v[158:159]
	v_lshlrev_b32_e32 v152, 16, v240
	v_and_b32_e32 v153, 0xffff0000, v240
	v_lshlrev_b32_e32 v154, 16, v241
	v_and_b32_e32 v155, 0xffff0000, v241
	v_lshlrev_b32_e32 v156, 16, v242
	v_and_b32_e32 v157, 0xffff0000, v242
	v_lshlrev_b32_e32 v158, 16, v243
	v_and_b32_e32 v159, 0xffff0000, v243
	v_pk_add_f32 v[20:21], v[20:21], v[152:153]
	v_pk_add_f32 v[22:23], v[22:23], v[154:155]
	v_pk_add_f32 v[16:17], v[16:17], v[156:157]
	v_pk_add_f32 v[18:19], v[18:19], v[158:159]
	v_cvt_pk_bf16_f32 v132, v20, v21
	v_cvt_pk_bf16_f32 v133, v22, v23
	v_cvt_pk_bf16_f32 v134, v16, v17
	v_cvt_pk_bf16_f32 v135, v18, v19
	global_store_dwordx4 v130, v[132:135], s[12:13]
	v_add_u32_e32 v130, 0x2000, v130
	s_waitcnt vmcnt(8)
	v_lshlrev_b32_e32 v152, 16, v188
	v_and_b32_e32 v153, 0xffff0000, v188
	v_lshlrev_b32_e32 v154, 16, v189
	v_and_b32_e32 v155, 0xffff0000, v189
	v_lshlrev_b32_e32 v156, 16, v190
	v_and_b32_e32 v157, 0xffff0000, v190
	v_lshlrev_b32_e32 v158, 16, v191
	v_and_b32_e32 v159, 0xffff0000, v191
	v_pk_mul_f32 v[12:13], v[12:13], v[152:153]
	v_pk_mul_f32 v[14:15], v[14:15], v[154:155]
	v_pk_mul_f32 v[8:9], v[8:9], v[156:157]
	v_pk_mul_f32 v[10:11], v[10:11], v[158:159]
	v_lshlrev_b32_e32 v152, 16, v192
	v_and_b32_e32 v153, 0xffff0000, v192
	v_lshlrev_b32_e32 v154, 16, v193
	v_and_b32_e32 v155, 0xffff0000, v193
	v_lshlrev_b32_e32 v156, 16, v194
	v_and_b32_e32 v157, 0xffff0000, v194
	v_lshlrev_b32_e32 v158, 16, v195
	v_and_b32_e32 v159, 0xffff0000, v195
	v_pk_add_f32 v[12:13], v[12:13], v[152:153]
	v_pk_add_f32 v[14:15], v[14:15], v[154:155]
	v_pk_add_f32 v[8:9], v[8:9], v[156:157]
	v_pk_add_f32 v[10:11], v[10:11], v[158:159]
	v_cvt_pk_bf16_f32 v132, v12, v13
	v_cvt_pk_bf16_f32 v133, v14, v15
	v_cvt_pk_bf16_f32 v134, v8, v9
	v_cvt_pk_bf16_f32 v135, v10, v11
	global_store_dwordx4 v130, v[132:135], s[12:13]
	v_add_u32_e32 v130, 0x2000, v130
	s_waitcnt vmcnt(6)
	v_lshlrev_b32_e32 v152, 16, v196
	v_and_b32_e32 v153, 0xffff0000, v196
	v_lshlrev_b32_e32 v154, 16, v197
	v_and_b32_e32 v155, 0xffff0000, v197
	v_lshlrev_b32_e32 v156, 16, v198
	v_and_b32_e32 v157, 0xffff0000, v198
	v_lshlrev_b32_e32 v158, 16, v199
	v_and_b32_e32 v159, 0xffff0000, v199
	v_pk_mul_f32 v[4:5], v[4:5], v[152:153]
	v_pk_mul_f32 v[6:7], v[6:7], v[154:155]
	v_pk_mul_f32 v[0:1], v[0:1], v[156:157]
	v_pk_mul_f32 v[2:3], v[2:3], v[158:159]
	v_lshlrev_b32_e32 v152, 16, v200
	v_and_b32_e32 v153, 0xffff0000, v200
	v_lshlrev_b32_e32 v154, 16, v201
	v_and_b32_e32 v155, 0xffff0000, v201
	v_lshlrev_b32_e32 v156, 16, v202
	v_and_b32_e32 v157, 0xffff0000, v202
	v_lshlrev_b32_e32 v158, 16, v203
	v_and_b32_e32 v159, 0xffff0000, v203
	v_pk_add_f32 v[4:5], v[4:5], v[152:153]
	v_pk_add_f32 v[6:7], v[6:7], v[154:155]
	v_pk_add_f32 v[0:1], v[0:1], v[156:157]
	v_pk_add_f32 v[2:3], v[2:3], v[158:159]
	v_cvt_pk_bf16_f32 v132, v4, v5
	v_cvt_pk_bf16_f32 v133, v6, v7
	v_cvt_pk_bf16_f32 v134, v0, v1
	v_cvt_pk_bf16_f32 v135, v2, v3
	global_store_dwordx4 v130, v[132:135], s[12:13]
	s_branch .LBB0_562
; __device__ __forceinline__ unsigned cvt_pk_bf16(float lo, float hi) { unsigned r; asm("v_cvt_pk_bf16_f32 %0, %1, %2" : "=v"(r) : "v"(lo), "v"(hi)); return r; }
; __device__ __forceinline__ float lo_bf(unsigned u) { return __uint_as_float(u << 16); }
; __device__ __forceinline__ float hi_bf(unsigned u) { return __uint_as_float(u & 0xffff0000u); }
;     __device__ __forceinline__ void operator()(f32x4 (&acc)[2][2][4][2], const GUnit& u, int wr, int wc, int fr, int fq, int tid) const {
;     ...
;                     for (int m = 0; m < 4; ++m) {
;                         const u32x4 g = ld_coh16(gp);
;                         u32x4 q = {0u, 0u, 0u, 0u}; if (sub != 1) q = ld_coh16(mp);
;                         f32x4 g0 = {lo_bf(g.x), hi_bf(g.x), lo_bf(g.y), hi_bf(g.y)}, g1 = {lo_bf(g.z), hi_bf(g.z), lo_bf(g.w), hi_bf(g.w)};
;                         f32x4 v0 = g0 * acc[ai][bj][m][0], v1 = g1 * acc[ai][bj][m][1];
;                         if (sub != 1) { v0 += (f32x4){lo_bf(q.x), hi_bf(q.x), lo_bf(q.y), hi_bf(q.y)}; v1 += (f32x4){lo_bf(q.z), hi_bf(q.z), lo_bf(q.w), hi_bf(q.w)}; }
;                         if (sub != 5) { u32x4 w; w.x = cvt_pk_bf16(v0[0], v0[1]); w.y = cvt_pk_bf16(v0[2], v0[3]); w.z = cvt_pk_bf16(v1[0], v1[1]); w.w = cvt_pk_bf16(v1[2], v1[3]); st_coh16(mp, w); }
;                         else { u32x4 w; w.x = cvt_pk_bf16(v0[0], v0[1]); w.y = cvt_pk_bf16(v0[2], v0[3]); w.z = cvt_pk_bf16(v1[0], v1[1]); w.w = cvt_pk_bf16(v1[2], v1[3]);
;                             *(u32x4*)(op + (size_t)(ai * HALF + m * 16) * DM + bj * HALF) = w; }
;                         gp += 4096; mp += 4096; asm volatile("" : "+v"(gp), "+v"(mp) :: "memory"); }
.Lbe_sub1:
	global_load_dwordx4 v[188:191], v129, s[22:23] sc1
	v_add_u32_e32 v129, 0x2000, v129
	global_load_dwordx4 v[196:199], v129, s[22:23] sc1
	v_add_u32_e32 v129, 0x2000, v129
	global_load_dwordx4 v[204:207], v129, s[22:23] sc1
	v_add_u32_e32 v129, 0x2000, v129
	global_load_dwordx4 v[212:215], v129, s[22:23] sc1
	v_add_u32_e32 v129, 0x2000, v129
	global_load_dwordx4 v[220:223], v129, s[22:23] sc1
	v_add_u32_e32 v129, 0x2000, v129
	global_load_dwordx4 v[228:231], v129, s[22:23] sc1
	v_add_u32_e32 v129, 0x2000, v129
	global_load_dwordx4 v[236:239], v129, s[22:23] sc1
	v_add_u32_e32 v129, 0x2000, v129
	s_waitcnt vmcnt(6)
	v_lshlrev_b32_e32 v152, 16, v188
	v_and_b32_e32 v153, 0xffff0000, v188
	v_lshlrev_b32_e32 v154, 16, v189
	v_and_b32_e32 v155, 0xffff0000, v189
	v_lshlrev_b32_e32 v156, 16, v190
	v_and_b32_e32 v157, 0xffff0000, v190
	v_lshlrev_b32_e32 v158, 16, v191
	v_and_b32_e32 v159, 0xffff0000, v191
	v_pk_mul_f32 v[124:125], v[124:125], v[152:153]
	v_pk_mul_f32 v[126:127], v[126:127], v[154:155]
	v_pk_mul_f32 v[120:121], v[120:121], v[156:157]
	v_pk_mul_f32 v[122:123], v[122:123], v[158:159]
	v_cvt_pk_bf16_f32 v132, v124, v125
	v_cvt_pk_bf16_f32 v133, v126, v127
	v_cvt_pk_bf16_f32 v134, v120, v121
	v_cvt_pk_bf16_f32 v135, v122, v123
	global_store_dwordx4 v130, v[132:135], s[12:13]
	v_add_u32_e32 v130, 0x2000, v130
	global_load_dwordx4 v[188:191], v129, s[22:23] sc1
	v_add_u32_e32 v129, 0x2000, v129
	s_waitcnt vmcnt(7)
	v_lshlrev_b32_e32 v152, 16, v196
	v_and_b32_e32 v153, 0xffff0000, v196
	v_lshlrev_b32_e32 v154, 16, v197
	v_and_b32_e32 v155, 0xffff0000, v197
	v_lshlrev_b32_e32 v156, 16, v198
	v_and_b32_e32 v157, 0xffff0000, v198
	v_lshlrev_b32_e32 v158, 16, v199
	v_and_b32_e32 v159, 0xffff0000, v199
	v_pk_mul_f32 v[116:117], v[116:117], v[152:153]
	v_pk_mul_f32 v[118:119], v[118:119], v[154:155]
	v_pk_mul_f32 v[112:113], v[112:113], v[156:157]
	v_pk_mul_f32 v[114:115], v[114:115], v[158:159]
	v_cvt_pk_bf16_f32 v132, v116, v117
	v_cvt_pk_bf16_f32 v133, v118, v119
	v_cvt_pk_bf16_f32 v134, v112, v113
	v_cvt_pk_bf16_f32 v135, v114, v115
	global_store_dwordx4 v130, v[132:135], s[12:13]
	v_add_u32_e32 v130, 0x2000, v130
	global_load_dwordx4 v[196:199], v129, s[22:23] sc1
	v_add_u32_e32 v129, 0x2000, v129
	s_waitcnt vmcnt(8)
	v_lshlrev_b32_e32 v152, 16, v204
	v_and_b32_e32 v153, 0xffff0000, v204
	v_lshlrev_b32_e32 v154, 16, v205
	v_and_b32_e32 v155, 0xffff0000, v205
	v_lshlrev_b32_e32 v156, 16, v206
	v_and_b32_e32 v157, 0xffff0000, v206
	v_lshlrev_b32_e32 v158, 16, v207
	v_and_b32_e32 v159, 0xffff0000, v207
	v_pk_mul_f32 v[108:109], v[108:109], v[152:153]
	v_pk_mul_f32 v[110:111], v[110:111], v[154:155]
	v_pk_mul_f32 v[104:105], v[104:105], v[156:157]
	v_pk_mul_f32 v[106:107], v[106:107], v[158:159]
	v_cvt_pk_bf16_f32 v132, v108, v109
	v_cvt_pk_bf16_f32 v133, v110, v111
	v_cvt_pk_bf16_f32 v134, v104, v105
	v_cvt_pk_bf16_f32 v135, v106, v107
	global_store_dwordx4 v130, v[132:135], s[12:13]
	v_add_u32_e32 v130, 0x2000, v130
	global_load_dwordx4 v[204:207], v129, s[22:23] sc1
	v_add_u32_e32 v129, 0x2000, v129
	s_waitcnt vmcnt(9)
	v_lshlrev_b32_e32 v152, 16, v212
	v_and_b32_e32 v153, 0xffff0000, v212
	v_lshlrev_b32_e32 v154, 16, v213
	v_and_b32_e32 v155, 0xffff0000, v213
	v_lshlrev_b32_e32 v156, 16, v214
	v_and_b32_e32 v157, 0xffff0000, v214
	v_lshlrev_b32_e32 v158, 16, v215
	v_and_b32_e32 v159, 0xffff0000, v215
	v_pk_mul_f32 v[100:101], v[100:101], v[152:153]
	v_pk_mul_f32 v[102:103], v[102:103], v[154:155]
	v_pk_mul_f32 v[96:97], v[96:97], v[156:157]
	v_pk_mul_f32 v[98:99], v[98:99], v[158:159]
	v_cvt_pk_bf16_f32 v132, v100, v101
	v_cvt_pk_bf16_f32 v133, v102, v103
	v_cvt_pk_bf16_f32 v134, v96, v97
	v_cvt_pk_bf16_f32 v135, v98, v99
	global_store_dwordx4 v130, v[132:135], s[12:13]
	v_add_u32_e32 v130, 0x2000, v130
	global_load_dwordx4 v[212:215], v129, s[22:23] sc1
	v_add_u32_e32 v129, 0x2000, v129
	s_waitcnt vmcnt(10)
	v_lshlrev_b32_e32 v152, 16, v220
	v_and_b32_e32 v153, 0xffff0000, v220
	v_lshlrev_b32_e32 v154, 16, v221
	v_and_b32_e32 v155, 0xffff0000, v221
	v_lshlrev_b32_e32 v156, 16, v222
	v_and_b32_e32 v157, 0xffff0000, v222
	v_lshlrev_b32_e32 v158, 16, v223
	v_and_b32_e32 v159, 0xffff0000, v223
	v_pk_mul_f32 v[92:93], v[92:93], v[152:153]
	v_pk_mul_f32 v[94:95], v[94:95], v[154:155]
	v_pk_mul_f32 v[88:89], v[88:89], v[156:157]
	v_pk_mul_f32 v[90:91], v[90:91], v[158:159]
	v_cvt_pk_bf16_f32 v132, v92, v93
	v_cvt_pk_bf16_f32 v133, v94, v95
	v_cvt_pk_bf16_f32 v134, v88, v89
	v_cvt_pk_bf16_f32 v135, v90, v91
	global_store_dwordx4 v130, v[132:135], s[12:13]
	v_add_u32_e32 v130, 0x2000, v130
	global_load_dwordx4 v[220:223], v129, s[22:23] sc1
	v_add_u32_e32 v129, 0x2000, v129
	s_waitcnt vmcnt(11)
	v_lshlrev_b32_e32 v152, 16, v228
	v_and_b32_e32 v153, 0xffff0000, v228
	v_lshlrev_b32_e32 v154, 16, v229
	v_and_b32_e32 v155, 0xffff0000, v229
	v_lshlrev_b32_e32 v156, 16, v230
	v_and_b32_e32 v157, 0xffff0000, v230
	v_lshlrev_b32_e32 v158, 16, v231
	v_and_b32_e32 v159, 0xffff0000, v231
	v_pk_mul_f32 v[84:85], v[84:85], v[152:153]
	v_pk_mul_f32 v[86:87], v[86:87], v[154:155]
	v_pk_mul_f32 v[80:81], v[80:81], v[156:157]
	v_pk_mul_f32 v[82:83], v[82:83], v[158:159]
	v_cvt_pk_bf16_f32 v132, v84, v85
	v_cvt_pk_bf16_f32 v133, v86, v87
	v_cvt_pk_bf16_f32 v134, v80, v81
	v_cvt_pk_bf16_f32 v135, v82, v83
	global_store_dwordx4 v130, v[132:135], s[12:13]
	v_add_u32_e32 v130, 0x2000, v130
	global_load_dwordx4 v[228:231], v129, s[22:23] sc1
	v_add_u32_e32 v129, 0x2000, v129
	s_waitcnt vmcnt(12)
; __device__ __forceinline__ unsigned cvt_pk_bf16(float lo, float hi) { unsigned r; asm("v_cvt_pk_bf16_f32 %0, %1, %2" : "=v"(r) : "v"(lo), "v"(hi)); return r; }
; __device__ __forceinline__ float lo_bf(unsigned u) { return __uint_as_float(u << 16); }
; __device__ __forceinline__ float hi_bf(unsigned u) { return __uint_as_float(u & 0xffff0000u); }
;     __device__ __forceinline__ void operator()(f32x4 (&acc)[2][2][4][2], const GUnit& u, int wr, int wc, int fr, int fq, int tid) const {
;     ...
;                     for (int m = 0; m < 4; ++m) {
;                         const u32x4 g = ld_coh16(gp);
;                         u32x4 q = {0u, 0u, 0u, 0u}; if (sub != 1) q = ld_coh16(mp);
;                         f32x4 g0 = {lo_bf(g.x), hi_bf(g.x), lo_bf(g.y), hi_bf(g.y)}, g1 = {lo_bf(g.z), hi_bf(g.z), lo_bf(g.w), hi_bf(g.w)};
;                         f32x4 v0 = g0 * acc[ai][bj][m][0], v1 = g1 * acc[ai][bj][m][1];
;                         if (sub != 1) { v0 += (f32x4){lo_bf(q.x), hi_bf(q.x), lo_bf(q.y), hi_bf(q.y)}; v1 += (f32x4){lo_bf(q.z), hi_bf(q.z), lo_bf(q.w), hi_bf(q.w)}; }
;                         if (sub != 5) { u32x4 w; w.x = cvt_pk_bf16(v0[0], v0[1]); w.y = cvt_pk_bf16(v0[2], v0[3]); w.z = cvt_pk_bf16(v1[0], v1[1]); w.w = cvt_pk_bf16(v1[2], v1[3]); st_coh16(mp, w); }
;                         else { u32x4 w; w.x = cvt_pk_bf16(v0[0], v0[1]); w.y = cvt_pk_bf16(v0[2], v0[3]); w.z = cvt_pk_bf16(v1[0], v1[1]); w.w = cvt_pk_bf16(v1[2], v1[3]);
;                             *(u32x4*)(op + (size_t)(ai * HALF + m * 16) * DM + bj * HALF) = w; }
;                         gp += 4096; mp += 4096; asm volatile("" : "+v"(gp), "+v"(mp) :: "memory"); }
	v_lshlrev_b32_e32 v152, 16, v236
	v_and_b32_e32 v153, 0xffff0000, v236
	v_lshlrev_b32_e32 v154, 16, v237
	v_and_b32_e32 v155, 0xffff0000, v237
	v_lshlrev_b32_e32 v156, 16, v238
	v_and_b32_e32 v157, 0xffff0000, v238
	v_lshlrev_b32_e32 v158, 16, v239
	v_and_b32_e32 v159, 0xffff0000, v239
	v_pk_mul_f32 v[76:77], v[76:77], v[152:153]
	v_pk_mul_f32 v[78:79], v[78:79], v[154:155]
	v_pk_mul_f32 v[72:73], v[72:73], v[156:157]
	v_pk_mul_f32 v[74:75], v[74:75], v[158:159]
	v_cvt_pk_bf16_f32 v132, v76, v77
	v_cvt_pk_bf16_f32 v133, v78, v79
	v_cvt_pk_bf16_f32 v134, v72, v73
	v_cvt_pk_bf16_f32 v135, v74, v75
	global_store_dwordx4 v130, v[132:135], s[12:13]
	v_add_u32_e32 v130, 0x2000, v130
	global_load_dwordx4 v[236:239], v129, s[22:23] sc1
	v_add_u32_e32 v129, 0x2000, v129
	s_waitcnt vmcnt(12)
	v_lshlrev_b32_e32 v152, 16, v188
	v_and_b32_e32 v153, 0xffff0000, v188
	v_lshlrev_b32_e32 v154, 16, v189
	v_and_b32_e32 v155, 0xffff0000, v189
	v_lshlrev_b32_e32 v156, 16, v190
	v_and_b32_e32 v157, 0xffff0000, v190
	v_lshlrev_b32_e32 v158, 16, v191
	v_and_b32_e32 v159, 0xffff0000, v191
	v_pk_mul_f32 v[68:69], v[68:69], v[152:153]
	v_pk_mul_f32 v[70:71], v[70:71], v[154:155]
	v_pk_mul_f32 v[64:65], v[64:65], v[156:157]
	v_pk_mul_f32 v[66:67], v[66:67], v[158:159]
	v_cvt_pk_bf16_f32 v132, v68, v69
	v_cvt_pk_bf16_f32 v133, v70, v71
	v_cvt_pk_bf16_f32 v134, v64, v65
	v_cvt_pk_bf16_f32 v135, v66, v67
	global_store_dwordx4 v130, v[132:135], s[12:13]
	v_add_u32_e32 v130, 0x2000, v130
	global_load_dwordx4 v[188:191], v129, s[22:23] sc1
	v_add_u32_e32 v129, 0x2000, v129
	s_waitcnt vmcnt(12)
	v_lshlrev_b32_e32 v152, 16, v196
	v_and_b32_e32 v153, 0xffff0000, v196
	v_lshlrev_b32_e32 v154, 16, v197
	v_and_b32_e32 v155, 0xffff0000, v197
	v_lshlrev_b32_e32 v156, 16, v198
	v_and_b32_e32 v157, 0xffff0000, v198
	v_lshlrev_b32_e32 v158, 16, v199
	v_and_b32_e32 v159, 0xffff0000, v199
	v_pk_mul_f32 v[60:61], v[60:61], v[152:153]
	v_pk_mul_f32 v[62:63], v[62:63], v[154:155]
	v_pk_mul_f32 v[56:57], v[56:57], v[156:157]
	v_pk_mul_f32 v[58:59], v[58:59], v[158:159]
	v_cvt_pk_bf16_f32 v132, v60, v61
	v_cvt_pk_bf16_f32 v133, v62, v63
	v_cvt_pk_bf16_f32 v134, v56, v57
	v_cvt_pk_bf16_f32 v135, v58, v59
	global_store_dwordx4 v130, v[132:135], s[12:13]
	v_add_u32_e32 v130, 0x2000, v130
	global_load_dwordx4 v[196:199], v129, s[22:23] sc1
	v_add_u32_e32 v129, 0x2000, v129
	s_waitcnt vmcnt(12)
	v_lshlrev_b32_e32 v152, 16, v204
	v_and_b32_e32 v153, 0xffff0000, v204
	v_lshlrev_b32_e32 v154, 16, v205
	v_and_b32_e32 v155, 0xffff0000, v205
	v_lshlrev_b32_e32 v156, 16, v206
	v_and_b32_e32 v157, 0xffff0000, v206
	v_lshlrev_b32_e32 v158, 16, v207
	v_and_b32_e32 v159, 0xffff0000, v207
	v_pk_mul_f32 v[52:53], v[52:53], v[152:153]
	v_pk_mul_f32 v[54:55], v[54:55], v[154:155]
	v_pk_mul_f32 v[48:49], v[48:49], v[156:157]
	v_pk_mul_f32 v[50:51], v[50:51], v[158:159]
	v_cvt_pk_bf16_f32 v132, v52, v53
	v_cvt_pk_bf16_f32 v133, v54, v55
	v_cvt_pk_bf16_f32 v134, v48, v49
	v_cvt_pk_bf16_f32 v135, v50, v51
	global_store_dwordx4 v130, v[132:135], s[12:13]
	v_add_u32_e32 v130, 0x2000, v130
	s_waitcnt vmcnt(11)
	v_lshlrev_b32_e32 v152, 16, v212
	v_and_b32_e32 v153, 0xffff0000, v212
	v_lshlrev_b32_e32 v154, 16, v213
	v_and_b32_e32 v155, 0xffff0000, v213
	v_lshlrev_b32_e32 v156, 16, v214
	v_and_b32_e32 v157, 0xffff0000, v214
	v_lshlrev_b32_e32 v158, 16, v215
	v_and_b32_e32 v159, 0xffff0000, v215
	v_pk_mul_f32 v[44:45], v[44:45], v[152:153]
	v_pk_mul_f32 v[46:47], v[46:47], v[154:155]
	v_pk_mul_f32 v[40:41], v[40:41], v[156:157]
	v_pk_mul_f32 v[42:43], v[42:43], v[158:159]
	v_cvt_pk_bf16_f32 v132, v44, v45
	v_cvt_pk_bf16_f32 v133, v46, v47
	v_cvt_pk_bf16_f32 v134, v40, v41
	v_cvt_pk_bf16_f32 v135, v42, v43
	global_store_dwordx4 v130, v[132:135], s[12:13]
	v_add_u32_e32 v130, 0x2000, v130
	s_waitcnt vmcnt(10)
; __device__ __forceinline__ unsigned cvt_pk_bf16(float lo, float hi) { unsigned r; asm("v_cvt_pk_bf16_f32 %0, %1, %2" : "=v"(r) : "v"(lo), "v"(hi)); return r; }
; __device__ __forceinline__ float lo_bf(unsigned u) { return __uint_as_float(u << 16); }
; __device__ __forceinline__ float hi_bf(unsigned u) { return __uint_as_float(u & 0xffff0000u); }
;     __device__ __forceinline__ void operator()(f32x4 (&acc)[2][2][4][2], const GUnit& u, int wr, int wc, int fr, int fq, int tid) const {
;     ...
;                     for (int m = 0; m < 4; ++m) {
;                         const u32x4 g = ld_coh16(gp);
;                         u32x4 q = {0u, 0u, 0u, 0u}; if (sub != 1) q = ld_coh16(mp);
;                         f32x4 g0 = {lo_bf(g.x), hi_bf(g.x), lo_bf(g.y), hi_bf(g.y)}, g1 = {lo_bf(g.z), hi_bf(g.z), lo_bf(g.w), hi_bf(g.w)};
;                         f32x4 v0 = g0 * acc[ai][bj][m][0], v1 = g1 * acc[ai][bj][m][1];
;                         if (sub != 1) { v0 += (f32x4){lo_bf(q.x), hi_bf(q.x), lo_bf(q.y), hi_bf(q.y)}; v1 += (f32x4){lo_bf(q.z), hi_bf(q.z), lo_bf(q.w), hi_bf(q.w)}; }
;                         if (sub != 5) { u32x4 w; w.x = cvt_pk_bf16(v0[0], v0[1]); w.y = cvt_pk_bf16(v0[2], v0[3]); w.z = cvt_pk_bf16(v1[0], v1[1]); w.w = cvt_pk_bf16(v1[2], v1[3]); st_coh16(mp, w); }
;                         else { u32x4 w; w.x = cvt_pk_bf16(v0[0], v0[1]); w.y = cvt_pk_bf16(v0[2], v0[3]); w.z = cvt_pk_bf16(v1[0], v1[1]); w.w = cvt_pk_bf16(v1[2], v1[3]);
;                             *(u32x4*)(op + (size_t)(ai * HALF + m * 16) * DM + bj * HALF) = w; }
;                         gp += 4096; mp += 4096; asm volatile("" : "+v"(gp), "+v"(mp) :: "memory"); }
	v_lshlrev_b32_e32 v152, 16, v220
	v_and_b32_e32 v153, 0xffff0000, v220
	v_lshlrev_b32_e32 v154, 16, v221
	v_and_b32_e32 v155, 0xffff0000, v221
	v_lshlrev_b32_e32 v156, 16, v222
	v_and_b32_e32 v157, 0xffff0000, v222
	v_lshlrev_b32_e32 v158, 16, v223
	v_and_b32_e32 v159, 0xffff0000, v223
	v_pk_mul_f32 v[36:37], v[36:37], v[152:153]
	v_pk_mul_f32 v[38:39], v[38:39], v[154:155]
	v_pk_mul_f32 v[32:33], v[32:33], v[156:157]
	v_pk_mul_f32 v[34:35], v[34:35], v[158:159]
	v_cvt_pk_bf16_f32 v132, v36, v37
	v_cvt_pk_bf16_f32 v133, v38, v39
	v_cvt_pk_bf16_f32 v134, v32, v33
	v_cvt_pk_bf16_f32 v135, v34, v35
	global_store_dwordx4 v130, v[132:135], s[12:13]
	v_add_u32_e32 v130, 0x2000, v130
	s_waitcnt vmcnt(9)
	v_lshlrev_b32_e32 v152, 16, v228
	v_and_b32_e32 v153, 0xffff0000, v228
	v_lshlrev_b32_e32 v154, 16, v229
	v_and_b32_e32 v155, 0xffff0000, v229
	v_lshlrev_b32_e32 v156, 16, v230
	v_and_b32_e32 v157, 0xffff0000, v230
	v_lshlrev_b32_e32 v158, 16, v231
	v_and_b32_e32 v159, 0xffff0000, v231
	v_pk_mul_f32 v[28:29], v[28:29], v[152:153]
	v_pk_mul_f32 v[30:31], v[30:31], v[154:155]
	v_pk_mul_f32 v[24:25], v[24:25], v[156:157]
	v_pk_mul_f32 v[26:27], v[26:27], v[158:159]
	v_cvt_pk_bf16_f32 v132, v28, v29
	v_cvt_pk_bf16_f32 v133, v30, v31
	v_cvt_pk_bf16_f32 v134, v24, v25
	v_cvt_pk_bf16_f32 v135, v26, v27
	global_store_dwordx4 v130, v[132:135], s[12:13]
	v_add_u32_e32 v130, 0x2000, v130
	s_waitcnt vmcnt(8)
	v_lshlrev_b32_e32 v152, 16, v236
	v_and_b32_e32 v153, 0xffff0000, v236
	v_lshlrev_b32_e32 v154, 16, v237
	v_and_b32_e32 v155, 0xffff0000, v237
	v_lshlrev_b32_e32 v156, 16, v238
	v_and_b32_e32 v157, 0xffff0000, v238
	v_lshlrev_b32_e32 v158, 16, v239
	v_and_b32_e32 v159, 0xffff0000, v239
	v_pk_mul_f32 v[20:21], v[20:21], v[152:153]
	v_pk_mul_f32 v[22:23], v[22:23], v[154:155]
	v_pk_mul_f32 v[16:17], v[16:17], v[156:157]
	v_pk_mul_f32 v[18:19], v[18:19], v[158:159]
	v_cvt_pk_bf16_f32 v132, v20, v21
	v_cvt_pk_bf16_f32 v133, v22, v23
	v_cvt_pk_bf16_f32 v134, v16, v17
	v_cvt_pk_bf16_f32 v135, v18, v19
	global_store_dwordx4 v130, v[132:135], s[12:13]
	v_add_u32_e32 v130, 0x2000, v130
	s_waitcnt vmcnt(7)
	v_lshlrev_b32_e32 v152, 16, v188
	v_and_b32_e32 v153, 0xffff0000, v188
	v_lshlrev_b32_e32 v154, 16, v189
	v_and_b32_e32 v155, 0xffff0000, v189
	v_lshlrev_b32_e32 v156, 16, v190
	v_and_b32_e32 v157, 0xffff0000, v190
	v_lshlrev_b32_e32 v158, 16, v191
	v_and_b32_e32 v159, 0xffff0000, v191
	v_pk_mul_f32 v[12:13], v[12:13], v[152:153]
	v_pk_mul_f32 v[14:15], v[14:15], v[154:155]
	v_pk_mul_f32 v[8:9], v[8:9], v[156:157]
	v_pk_mul_f32 v[10:11], v[10:11], v[158:159]
	v_cvt_pk_bf16_f32 v132, v12, v13
	v_cvt_pk_bf16_f32 v133, v14, v15
	v_cvt_pk_bf16_f32 v134, v8, v9
	v_cvt_pk_bf16_f32 v135, v10, v11
	global_store_dwordx4 v130, v[132:135], s[12:13]
	v_add_u32_e32 v130, 0x2000, v130
	s_waitcnt vmcnt(6)
	v_lshlrev_b32_e32 v152, 16, v196
	v_and_b32_e32 v153, 0xffff0000, v196
	v_lshlrev_b32_e32 v154, 16, v197
	v_and_b32_e32 v155, 0xffff0000, v197
	v_lshlrev_b32_e32 v156, 16, v198
	v_and_b32_e32 v157, 0xffff0000, v198
	v_lshlrev_b32_e32 v158, 16, v199
	v_and_b32_e32 v159, 0xffff0000, v199
	v_pk_mul_f32 v[4:5], v[4:5], v[152:153]
	v_pk_mul_f32 v[6:7], v[6:7], v[154:155]
	v_pk_mul_f32 v[0:1], v[0:1], v[156:157]
	v_pk_mul_f32 v[2:3], v[2:3], v[158:159]
	v_cvt_pk_bf16_f32 v132, v4, v5
	v_cvt_pk_bf16_f32 v133, v6, v7
	v_cvt_pk_bf16_f32 v134, v0, v1
	v_cvt_pk_bf16_f32 v135, v2, v3
	global_store_dwordx4 v130, v[132:135], s[12:13]
	s_branch .LBB0_562

; __device__ __forceinline__ unsigned cvt_pk_bf16(float lo, float hi) { unsigned r; asm("v_cvt_pk_bf16_f32 %0, %1, %2" : "=v"(r) : "v"(lo), "v"(hi)); return r; }
; __device__ __forceinline__ float sigmoidf_(float x) { return __builtin_amdgcn_rcpf(1.0f + __expf(-x)); }
;     __device__ __forceinline__ void operator()(f32x4 (&acc)[2][2][4][2], const GUnit& u, int wr, int wc, int fr, int fq, int tid) const {
;     ...
;         if ((sub & 1) == 0) {
;             const float* bp = bgate + br * 2048 + u.pn * BM + wc * 32 + 8 * fq;
; #pragma unroll
;             for (int ai = 0; ai < 2; ++ai)
; #pragma unroll
;                 for (int bj = 0; bj < 2; ++bj) { const f32x4 b0 = *(const f32x4*)(bp + bj * HALF), b1 = *(const f32x4*)(bp + bj * HALF + 4);
; #pragma unroll
;                     for (int m = 0; m < 4; ++m) { f32x4 v0 = acc[ai][bj][m][0] + b0, v1 = acc[ai][bj][m][1] + b1;
; #pragma unroll
;                         for (int j = 0; j < 4; ++j) { v0[j] = sigmoidf_(v0[j]); v1[j] = sigmoidf_(v1[j]); }
;                         u32x4 w; w.x = cvt_pk_bf16(v0[0], v0[1]); w.y = cvt_pk_bf16(v0[2], v0[3]); w.z = cvt_pk_bf16(v1[0], v1[1]); w.w = cvt_pk_bf16(v1[2], v1[3]);
;                         st_coh16(gp, w); gp += 4096; asm volatile("" : "+v"(gp) :: "memory"); } }
.LBB0_679:
	s_and_b64 vcc, exec, s[12:13]
	s_cbranch_vccz .LBB0_562
	s_lshl_b32 s12, s96, 10
	s_ashr_i32 s13, s12, 31
	s_lshl_b64 s[12:13], s[12:13], 2
	v_readlane_b32 s14, v254, 50
	s_add_u32 s14, s14, s12
	v_readlane_b32 s12, v255, 21
	s_addc_u32 s15, s12, s13
	s_lshl_b32 s12, s97, 8
	s_ashr_i32 s13, s12, 31
	s_lshl_b64 s[12:13], s[12:13], 2
	s_add_u32 s12, s14, s12
	s_addc_u32 s13, s15, s13
	s_lshl_b32 s14, s20, 2
	s_add_u32 s12, s12, s14
	v_lshlrev_b32_e32 v128, 3, v136
	s_addc_u32 s13, s13, 0
	v_ashrrev_i32_e32 v129, 31, v128
	v_lshl_add_u64 v[152:153], v[128:129], 2, s[12:13]
	global_load_dwordx4 v[128:131], v[152:153], off offset:16
	global_load_dwordx4 v[132:135], v[152:153], off
	global_load_dwordx4 v[188:191], v[152:153], off offset:528
	global_load_dwordx4 v[192:195], v[152:153], off offset:512
	global_load_dwordx4 v[196:199], v[152:153], off offset:16
	global_load_dwordx4 v[200:203], v[152:153], off
	s_waitcnt vmcnt(0)
	v_pk_add_f32 v[122:123], v[122:123], v[130:131]
	v_pk_add_f32 v[120:121], v[120:121], v[128:129]
	v_mul_f32_e32 v122, 0xbfb8aa3b, v122
	v_mul_f32_e32 v120, 0xbfb8aa3b, v120
	v_mul_f32_e32 v121, 0xbfb8aa3b, v121
	v_exp_f32_e32 v120, v120
	v_exp_f32_e32 v121, v121
	v_exp_f32_e32 v122, v122
	v_pk_add_f32 v[126:127], v[126:127], v[134:135]
	v_pk_add_f32 v[124:125], v[124:125], v[132:133]
	v_add_f32_e32 v120, 1.0, v120
	v_add_f32_e32 v121, 1.0, v121
	v_add_f32_e32 v122, 1.0, v122
	v_rcp_f32_e32 v136, v120
	v_mul_f32_e32 v120, 0xbfb8aa3b, v125
	v_rcp_f32_e32 v125, v121
	v_mul_f32_e32 v121, 0xbfb8aa3b, v126
	v_rcp_f32_e32 v126, v122
	v_mul_f32_e32 v122, 0xbfb8aa3b, v127
	v_mul_f32_e32 v124, 0xbfb8aa3b, v124
	v_exp_f32_e32 v120, v120
	v_exp_f32_e32 v121, v121
	v_exp_f32_e32 v122, v122
	v_mul_f32_e32 v123, 0xbfb8aa3b, v123
	v_pk_add_f32 v[114:115], v[114:115], v[130:131]
	v_pk_add_f32 v[112:113], v[112:113], v[128:129]
	v_exp_f32_e32 v124, v124
	v_exp_f32_e32 v123, v123
	v_mul_f32_e32 v112, 0xbfb8aa3b, v112
	v_mul_f32_e32 v113, 0xbfb8aa3b, v113
	v_mul_f32_e32 v114, 0xbfb8aa3b, v114
	v_exp_f32_e32 v112, v112
	v_exp_f32_e32 v113, v113
	v_exp_f32_e32 v114, v114
	v_add_f32_e32 v120, 1.0, v120
	v_add_f32_e32 v121, 1.0, v121
	v_add_f32_e32 v122, 1.0, v122
	v_add_f32_e32 v124, 1.0, v124
	v_rcp_f32_e32 v120, v120
	v_rcp_f32_e32 v121, v121
	v_rcp_f32_e32 v122, v122
	v_add_f32_e32 v123, 1.0, v123
	v_rcp_f32_e32 v124, v124
	v_rcp_f32_e32 v123, v123
	v_cvt_pk_bf16_f32 v120, v124, v120
	v_cvt_pk_bf16_f32 v121, v121, v122
	v_cvt_pk_bf16_f32 v122, v136, v125
	v_pk_add_f32 v[118:119], v[118:119], v[134:135]
	v_pk_add_f32 v[116:117], v[116:117], v[132:133]
	v_add_f32_e32 v112, 1.0, v112
	v_add_f32_e32 v113, 1.0, v113
	v_add_f32_e32 v114, 1.0, v114
	v_cvt_pk_bf16_f32 v123, v126, v123
	global_store_dwordx2 v[150:151], v[120:121], off
	global_store_dwordx2 v[150:151], v[122:123], off offset:8
	v_rcp_f32_e32 v122, v112
	v_mul_f32_e32 v112, 0xbfb8aa3b, v117
	v_rcp_f32_e32 v117, v113
	v_mul_f32_e32 v113, 0xbfb8aa3b, v118
	v_rcp_f32_e32 v118, v114
	v_mul_f32_e32 v114, 0xbfb8aa3b, v119
	v_mul_f32_e32 v116, 0xbfb8aa3b, v116
	v_exp_f32_e32 v112, v112
	v_exp_f32_e32 v113, v113
	v_exp_f32_e32 v114, v114
	v_mul_f32_e32 v115, 0xbfb8aa3b, v115
	v_pk_add_f32 v[106:107], v[106:107], v[130:131]
	v_pk_add_f32 v[104:105], v[104:105], v[128:129]
	v_exp_f32_e32 v116, v116
	v_exp_f32_e32 v115, v115
	v_mul_f32_e32 v104, 0xbfb8aa3b, v104
	v_mul_f32_e32 v105, 0xbfb8aa3b, v105
	v_mul_f32_e32 v106, 0xbfb8aa3b, v106
	v_lshl_add_u64 v[120:121], v[150:151], 0, s[86:87]
	v_exp_f32_e32 v104, v104
	v_exp_f32_e32 v105, v105
	v_exp_f32_e32 v106, v106
	v_add_f32_e32 v112, 1.0, v112
	v_add_f32_e32 v113, 1.0, v113
	v_add_f32_e32 v114, 1.0, v114
	v_add_f32_e32 v116, 1.0, v116
	v_rcp_f32_e32 v112, v112
	v_rcp_f32_e32 v113, v113
	v_rcp_f32_e32 v114, v114
	v_add_f32_e32 v115, 1.0, v115
	v_rcp_f32_e32 v116, v116
	v_rcp_f32_e32 v115, v115
	v_cvt_pk_bf16_f32 v112, v116, v112
	v_cvt_pk_bf16_f32 v113, v113, v114
	v_cvt_pk_bf16_f32 v114, v122, v117
	v_pk_add_f32 v[110:111], v[110:111], v[134:135]
	v_pk_add_f32 v[108:109], v[108:109], v[132:133]
	v_add_f32_e32 v104, 1.0, v104
	v_add_f32_e32 v105, 1.0, v105
	v_add_f32_e32 v106, 1.0, v106
	v_cvt_pk_bf16_f32 v115, v118, v115
	flat_store_dwordx2 v[120:121], v[112:113]
	flat_store_dwordx2 v[120:121], v[114:115] offset:8
	v_rcp_f32_e32 v114, v104
	v_mul_f32_e32 v104, 0xbfb8aa3b, v109
	v_rcp_f32_e32 v109, v105
	v_mul_f32_e32 v105, 0xbfb8aa3b, v110
	v_rcp_f32_e32 v110, v106
	v_mul_f32_e32 v106, 0xbfb8aa3b, v111
	v_mul_f32_e32 v108, 0xbfb8aa3b, v108
	v_exp_f32_e32 v104, v104
	v_exp_f32_e32 v105, v105
	v_exp_f32_e32 v106, v106
	v_mul_f32_e32 v107, 0xbfb8aa3b, v107
	v_pk_add_f32 v[96:97], v[96:97], v[128:129]
	v_exp_f32_e32 v108, v108
	v_exp_f32_e32 v107, v107
	v_pk_add_f32 v[98:99], v[98:99], v[130:131]
	v_mul_f32_e32 v96, 0xbfb8aa3b, v96
	v_mul_f32_e32 v97, 0xbfb8aa3b, v97
	v_lshl_add_u64 v[112:113], v[120:121], 0, s[86:87]
	v_exp_f32_e32 v96, v96
	v_exp_f32_e32 v97, v97
	v_mul_f32_e32 v98, 0xbfb8aa3b, v98
	v_exp_f32_e32 v98, v98
	v_add_f32_e32 v104, 1.0, v104
	v_add_f32_e32 v105, 1.0, v105
	v_add_f32_e32 v106, 1.0, v106
	v_add_f32_e32 v108, 1.0, v108
	v_rcp_f32_e32 v104, v104
	v_rcp_f32_e32 v105, v105
	v_rcp_f32_e32 v106, v106
	v_add_f32_e32 v107, 1.0, v107
	v_rcp_f32_e32 v108, v108
	v_rcp_f32_e32 v107, v107
	v_cvt_pk_bf16_f32 v104, v108, v104
	v_cvt_pk_bf16_f32 v105, v105, v106
	v_cvt_pk_bf16_f32 v106, v114, v109
	v_pk_add_f32 v[102:103], v[102:103], v[134:135]
	v_pk_add_f32 v[100:101], v[100:101], v[132:133]
	v_add_f32_e32 v96, 1.0, v96
	v_add_f32_e32 v97, 1.0, v97
	v_cvt_pk_bf16_f32 v107, v110, v107
	flat_store_dwordx2 v[112:113], v[104:105]
; __device__ __forceinline__ unsigned cvt_pk_bf16(float lo, float hi) { unsigned r; asm("v_cvt_pk_bf16_f32 %0, %1, %2" : "=v"(r) : "v"(lo), "v"(hi)); return r; }
; __device__ __forceinline__ float sigmoidf_(float x) { return __builtin_amdgcn_rcpf(1.0f + __expf(-x)); }
;     __device__ __forceinline__ void operator()(f32x4 (&acc)[2][2][4][2], const GUnit& u, int wr, int wc, int fr, int fq, int tid) const {
;     ...
;                 for (int bj = 0; bj < 2; ++bj) { const f32x4 b0 = *(const f32x4*)(bp + bj * HALF), b1 = *(const f32x4*)(bp + bj * HALF + 4);
; #pragma unroll
;                     for (int m = 0; m < 4; ++m) { f32x4 v0 = acc[ai][bj][m][0] + b0, v1 = acc[ai][bj][m][1] + b1;
; #pragma unroll
;                         for (int j = 0; j < 4; ++j) { v0[j] = sigmoidf_(v0[j]); v1[j] = sigmoidf_(v1[j]); }
;                         u32x4 w; w.x = cvt_pk_bf16(v0[0], v0[1]); w.y = cvt_pk_bf16(v0[2], v0[3]); w.z = cvt_pk_bf16(v1[0], v1[1]); w.w = cvt_pk_bf16(v1[2], v1[3]);
;                         st_coh16(gp, w); gp += 4096; asm volatile("" : "+v"(gp) :: "memory"); } }
	flat_store_dwordx2 v[112:113], v[106:107] offset:8
	v_rcp_f32_e32 v106, v96
	v_mul_f32_e32 v96, 0xbfb8aa3b, v101
	v_rcp_f32_e32 v101, v97
	v_mul_f32_e32 v97, 0xbfb8aa3b, v102
	v_add_f32_e32 v98, 1.0, v98
	v_mul_f32_e32 v100, 0xbfb8aa3b, v100
	v_exp_f32_e32 v96, v96
	v_exp_f32_e32 v97, v97
	v_rcp_f32_e32 v102, v98
	v_mul_f32_e32 v98, 0xbfb8aa3b, v103
	v_mul_f32_e32 v99, 0xbfb8aa3b, v99
	v_exp_f32_e32 v100, v100
	v_exp_f32_e32 v98, v98
	v_exp_f32_e32 v99, v99
	v_lshl_add_u64 v[104:105], v[112:113], 0, s[86:87]
	v_add_f32_e32 v96, 1.0, v96
	v_add_f32_e32 v97, 1.0, v97
	v_add_f32_e32 v100, 1.0, v100
	v_rcp_f32_e32 v96, v96
	v_rcp_f32_e32 v97, v97
	v_add_f32_e32 v98, 1.0, v98
	v_add_f32_e32 v99, 1.0, v99
	v_rcp_f32_e32 v100, v100
	v_rcp_f32_e32 v98, v98
	v_rcp_f32_e32 v99, v99
	v_cvt_pk_bf16_f32 v96, v100, v96
	v_cvt_pk_bf16_f32 v97, v97, v98
	v_cvt_pk_bf16_f32 v98, v106, v101
	v_cvt_pk_bf16_f32 v99, v102, v99
	flat_store_dwordx2 v[104:105], v[96:97]
	flat_store_dwordx2 v[104:105], v[98:99] offset:8
	v_lshl_add_u64 v[104:105], v[104:105], 0, s[86:87]
	s_nop 1
	v_mov_b32_e32 v96, v188
	v_mov_b32_e32 v97, v189
	v_mov_b32_e32 v98, v190
	v_mov_b32_e32 v99, v191
	v_mov_b32_e32 v100, v192
	v_mov_b32_e32 v101, v193
	v_mov_b32_e32 v102, v194
	v_mov_b32_e32 v103, v195
	v_pk_add_f32 v[90:91], v[90:91], v[98:99]
	v_pk_add_f32 v[88:89], v[88:89], v[96:97]
	v_mul_f32_e32 v90, 0xbfb8aa3b, v90
	v_mul_f32_e32 v88, 0xbfb8aa3b, v88
	v_mul_f32_e32 v89, 0xbfb8aa3b, v89
	v_exp_f32_e32 v88, v88
	v_exp_f32_e32 v89, v89
	v_exp_f32_e32 v90, v90
	v_pk_add_f32 v[94:95], v[94:95], v[102:103]
	v_pk_add_f32 v[92:93], v[92:93], v[100:101]
	v_add_f32_e32 v88, 1.0, v88
	v_add_f32_e32 v89, 1.0, v89
	v_add_f32_e32 v90, 1.0, v90
	v_rcp_f32_e32 v106, v88
	v_mul_f32_e32 v88, 0xbfb8aa3b, v93
	v_rcp_f32_e32 v93, v89
	v_mul_f32_e32 v89, 0xbfb8aa3b, v94
	v_rcp_f32_e32 v94, v90
	v_mul_f32_e32 v90, 0xbfb8aa3b, v95
	v_mul_f32_e32 v92, 0xbfb8aa3b, v92
	v_exp_f32_e32 v88, v88
	v_exp_f32_e32 v89, v89
	v_exp_f32_e32 v90, v90
	v_mul_f32_e32 v91, 0xbfb8aa3b, v91
	v_pk_add_f32 v[82:83], v[82:83], v[98:99]
	v_pk_add_f32 v[80:81], v[80:81], v[96:97]
	v_exp_f32_e32 v92, v92
	v_exp_f32_e32 v91, v91
	v_mul_f32_e32 v80, 0xbfb8aa3b, v80
	v_mul_f32_e32 v81, 0xbfb8aa3b, v81
	v_mul_f32_e32 v82, 0xbfb8aa3b, v82
	v_exp_f32_e32 v80, v80
	v_exp_f32_e32 v81, v81
	v_exp_f32_e32 v82, v82
	v_add_f32_e32 v88, 1.0, v88
	v_add_f32_e32 v89, 1.0, v89
	v_add_f32_e32 v90, 1.0, v90
	v_add_f32_e32 v92, 1.0, v92
	v_rcp_f32_e32 v88, v88
	v_rcp_f32_e32 v89, v89
	v_rcp_f32_e32 v90, v90
	v_add_f32_e32 v91, 1.0, v91
	v_rcp_f32_e32 v92, v92
	v_rcp_f32_e32 v91, v91
	v_cvt_pk_bf16_f32 v88, v92, v88
	v_cvt_pk_bf16_f32 v89, v89, v90
	v_cvt_pk_bf16_f32 v90, v106, v93
	v_pk_add_f32 v[86:87], v[86:87], v[102:103]
	v_pk_add_f32 v[84:85], v[84:85], v[100:101]
	v_add_f32_e32 v80, 1.0, v80
	v_add_f32_e32 v81, 1.0, v81
	v_add_f32_e32 v82, 1.0, v82
	v_cvt_pk_bf16_f32 v91, v94, v91
	flat_store_dwordx2 v[104:105], v[88:89]
	flat_store_dwordx2 v[104:105], v[90:91] offset:8
	v_rcp_f32_e32 v90, v80
	v_mul_f32_e32 v80, 0xbfb8aa3b, v85
	v_rcp_f32_e32 v85, v81
	v_mul_f32_e32 v81, 0xbfb8aa3b, v86
	v_rcp_f32_e32 v86, v82
	v_mul_f32_e32 v82, 0xbfb8aa3b, v87
	v_mul_f32_e32 v84, 0xbfb8aa3b, v84
	v_exp_f32_e32 v80, v80
	v_exp_f32_e32 v81, v81
	v_exp_f32_e32 v82, v82
	v_mul_f32_e32 v83, 0xbfb8aa3b, v83
	v_pk_add_f32 v[74:75], v[74:75], v[98:99]
	v_pk_add_f32 v[72:73], v[72:73], v[96:97]
	v_exp_f32_e32 v84, v84
	v_exp_f32_e32 v83, v83
	v_mul_f32_e32 v72, 0xbfb8aa3b, v72
	v_mul_f32_e32 v73, 0xbfb8aa3b, v73
	v_mul_f32_e32 v74, 0xbfb8aa3b, v74
	v_lshl_add_u64 v[88:89], v[104:105], 0, s[86:87]
	v_exp_f32_e32 v72, v72
	v_exp_f32_e32 v73, v73
	v_exp_f32_e32 v74, v74
	v_add_f32_e32 v80, 1.0, v80
	v_add_f32_e32 v81, 1.0, v81
	v_add_f32_e32 v82, 1.0, v82
	v_add_f32_e32 v84, 1.0, v84
	v_rcp_f32_e32 v80, v80
	v_rcp_f32_e32 v81, v81
	v_rcp_f32_e32 v82, v82
	v_add_f32_e32 v83, 1.0, v83
	v_rcp_f32_e32 v84, v84
	v_rcp_f32_e32 v83, v83
	v_cvt_pk_bf16_f32 v80, v84, v80
	v_cvt_pk_bf16_f32 v81, v81, v82
	v_cvt_pk_bf16_f32 v82, v90, v85
	v_pk_add_f32 v[78:79], v[78:79], v[102:103]
	v_pk_add_f32 v[76:77], v[76:77], v[100:101]
	v_add_f32_e32 v72, 1.0, v72
	v_add_f32_e32 v73, 1.0, v73
	v_add_f32_e32 v74, 1.0, v74
	v_cvt_pk_bf16_f32 v83, v86, v83
	flat_store_dwordx2 v[88:89], v[80:81]
	flat_store_dwordx2 v[88:89], v[82:83] offset:8
	v_rcp_f32_e32 v82, v72
	v_mul_f32_e32 v72, 0xbfb8aa3b, v77
	v_rcp_f32_e32 v77, v73
	v_mul_f32_e32 v73, 0xbfb8aa3b, v78
	v_rcp_f32_e32 v78, v74
	v_mul_f32_e32 v74, 0xbfb8aa3b, v79
	v_mul_f32_e32 v76, 0xbfb8aa3b, v76
	v_exp_f32_e32 v72, v72
	v_exp_f32_e32 v73, v73
	v_exp_f32_e32 v74, v74
	v_mul_f32_e32 v75, 0xbfb8aa3b, v75
	v_pk_add_f32 v[64:65], v[64:65], v[96:97]
	v_exp_f32_e32 v76, v76
	v_exp_f32_e32 v75, v75
	v_pk_add_f32 v[66:67], v[66:67], v[98:99]
	v_mul_f32_e32 v64, 0xbfb8aa3b, v64
	v_mul_f32_e32 v65, 0xbfb8aa3b, v65
	v_lshl_add_u64 v[80:81], v[88:89], 0, s[86:87]
	v_exp_f32_e32 v64, v64
	v_exp_f32_e32 v65, v65
	v_mul_f32_e32 v66, 0xbfb8aa3b, v66
	v_exp_f32_e32 v66, v66
	v_add_f32_e32 v72, 1.0, v72
	v_add_f32_e32 v73, 1.0, v73
	v_add_f32_e32 v74, 1.0, v74
	v_add_f32_e32 v76, 1.0, v76
	v_rcp_f32_e32 v72, v72
	v_rcp_f32_e32 v73, v73
	v_rcp_f32_e32 v74, v74
	v_add_f32_e32 v75, 1.0, v75
	v_rcp_f32_e32 v76, v76
	v_rcp_f32_e32 v75, v75
	v_cvt_pk_bf16_f32 v72, v76, v72
	v_cvt_pk_bf16_f32 v73, v73, v74
	v_cvt_pk_bf16_f32 v74, v82, v77
	v_pk_add_f32 v[70:71], v[70:71], v[102:103]
	v_pk_add_f32 v[68:69], v[68:69], v[100:101]
	v_add_f32_e32 v64, 1.0, v64
	v_add_f32_e32 v65, 1.0, v65
	v_cvt_pk_bf16_f32 v75, v78, v75
	flat_store_dwordx2 v[80:81], v[72:73]
; __device__ __forceinline__ unsigned cvt_pk_bf16(float lo, float hi) { unsigned r; asm("v_cvt_pk_bf16_f32 %0, %1, %2" : "=v"(r) : "v"(lo), "v"(hi)); return r; }
; __device__ __forceinline__ float sigmoidf_(float x) { return __builtin_amdgcn_rcpf(1.0f + __expf(-x)); }
;     __device__ __forceinline__ void operator()(f32x4 (&acc)[2][2][4][2], const GUnit& u, int wr, int wc, int fr, int fq, int tid) const {
;     ...
;                 for (int bj = 0; bj < 2; ++bj) { const f32x4 b0 = *(const f32x4*)(bp + bj * HALF), b1 = *(const f32x4*)(bp + bj * HALF + 4);
; #pragma unroll
;                     for (int m = 0; m < 4; ++m) { f32x4 v0 = acc[ai][bj][m][0] + b0, v1 = acc[ai][bj][m][1] + b1;
; #pragma unroll
;                         for (int j = 0; j < 4; ++j) { v0[j] = sigmoidf_(v0[j]); v1[j] = sigmoidf_(v1[j]); }
;                         u32x4 w; w.x = cvt_pk_bf16(v0[0], v0[1]); w.y = cvt_pk_bf16(v0[2], v0[3]); w.z = cvt_pk_bf16(v1[0], v1[1]); w.w = cvt_pk_bf16(v1[2], v1[3]);
;                         st_coh16(gp, w); gp += 4096; asm volatile("" : "+v"(gp) :: "memory"); } }
	flat_store_dwordx2 v[80:81], v[74:75] offset:8
	v_rcp_f32_e32 v74, v64
	v_mul_f32_e32 v64, 0xbfb8aa3b, v69
	v_rcp_f32_e32 v69, v65
	v_mul_f32_e32 v65, 0xbfb8aa3b, v70
	v_add_f32_e32 v66, 1.0, v66
	v_mul_f32_e32 v68, 0xbfb8aa3b, v68
	v_exp_f32_e32 v64, v64
	v_exp_f32_e32 v65, v65
	v_rcp_f32_e32 v70, v66
	v_mul_f32_e32 v66, 0xbfb8aa3b, v71
	v_mul_f32_e32 v67, 0xbfb8aa3b, v67
	v_exp_f32_e32 v68, v68
	v_exp_f32_e32 v66, v66
	v_exp_f32_e32 v67, v67
	v_lshl_add_u64 v[72:73], v[80:81], 0, s[86:87]
	v_add_f32_e32 v64, 1.0, v64
	v_add_f32_e32 v65, 1.0, v65
	v_add_f32_e32 v68, 1.0, v68
	v_rcp_f32_e32 v64, v64
	v_rcp_f32_e32 v65, v65
	v_add_f32_e32 v66, 1.0, v66
	v_add_f32_e32 v67, 1.0, v67
	v_rcp_f32_e32 v68, v68
	v_rcp_f32_e32 v66, v66
	v_rcp_f32_e32 v67, v67
	v_cvt_pk_bf16_f32 v64, v68, v64
	v_cvt_pk_bf16_f32 v65, v65, v66
	v_cvt_pk_bf16_f32 v66, v74, v69
	v_cvt_pk_bf16_f32 v67, v70, v67
	flat_store_dwordx2 v[72:73], v[64:65]
	flat_store_dwordx2 v[72:73], v[66:67] offset:8
	v_lshl_add_u64 v[72:73], v[72:73], 0, s[86:87]
	s_nop 1
	v_mov_b32_e32 v64, v196
	v_mov_b32_e32 v65, v197
	v_mov_b32_e32 v66, v198
	v_mov_b32_e32 v67, v199
	v_mov_b32_e32 v68, v200
	v_mov_b32_e32 v69, v201
	v_mov_b32_e32 v70, v202
	v_mov_b32_e32 v71, v203
	v_pk_add_f32 v[58:59], v[58:59], v[66:67]
	v_pk_add_f32 v[56:57], v[56:57], v[64:65]
	v_mul_f32_e32 v58, 0xbfb8aa3b, v58
	v_mul_f32_e32 v56, 0xbfb8aa3b, v56
	v_mul_f32_e32 v57, 0xbfb8aa3b, v57
	v_exp_f32_e32 v56, v56
	v_exp_f32_e32 v57, v57
	v_exp_f32_e32 v58, v58
	v_pk_add_f32 v[62:63], v[62:63], v[70:71]
	v_pk_add_f32 v[60:61], v[60:61], v[68:69]
	v_add_f32_e32 v56, 1.0, v56
	v_add_f32_e32 v57, 1.0, v57
	v_add_f32_e32 v58, 1.0, v58
	v_rcp_f32_e32 v74, v56
	v_mul_f32_e32 v56, 0xbfb8aa3b, v61
	v_rcp_f32_e32 v61, v57
	v_mul_f32_e32 v57, 0xbfb8aa3b, v62
	v_rcp_f32_e32 v62, v58
	v_mul_f32_e32 v58, 0xbfb8aa3b, v63
	v_mul_f32_e32 v60, 0xbfb8aa3b, v60
	v_exp_f32_e32 v56, v56
	v_exp_f32_e32 v57, v57
	v_exp_f32_e32 v58, v58
	v_mul_f32_e32 v59, 0xbfb8aa3b, v59
	v_pk_add_f32 v[50:51], v[50:51], v[66:67]
	v_pk_add_f32 v[48:49], v[48:49], v[64:65]
	v_exp_f32_e32 v60, v60
	v_exp_f32_e32 v59, v59
	v_mul_f32_e32 v48, 0xbfb8aa3b, v48
	v_mul_f32_e32 v49, 0xbfb8aa3b, v49
	v_mul_f32_e32 v50, 0xbfb8aa3b, v50
	v_exp_f32_e32 v48, v48
	v_exp_f32_e32 v49, v49
	v_exp_f32_e32 v50, v50
	v_add_f32_e32 v56, 1.0, v56
	v_add_f32_e32 v57, 1.0, v57
	v_add_f32_e32 v58, 1.0, v58
	v_add_f32_e32 v60, 1.0, v60
	v_rcp_f32_e32 v56, v56
	v_rcp_f32_e32 v57, v57
	v_rcp_f32_e32 v58, v58
	v_add_f32_e32 v59, 1.0, v59
	v_rcp_f32_e32 v60, v60
	v_rcp_f32_e32 v59, v59
	v_cvt_pk_bf16_f32 v56, v60, v56
	v_cvt_pk_bf16_f32 v57, v57, v58
	v_cvt_pk_bf16_f32 v58, v74, v61
	v_pk_add_f32 v[54:55], v[54:55], v[70:71]
	v_pk_add_f32 v[52:53], v[52:53], v[68:69]
	v_add_f32_e32 v48, 1.0, v48
	v_add_f32_e32 v49, 1.0, v49
	v_add_f32_e32 v50, 1.0, v50
	v_cvt_pk_bf16_f32 v59, v62, v59
	flat_store_dwordx2 v[72:73], v[56:57]
	flat_store_dwordx2 v[72:73], v[58:59] offset:8
	v_rcp_f32_e32 v58, v48
	v_mul_f32_e32 v48, 0xbfb8aa3b, v53
	v_rcp_f32_e32 v53, v49
	v_mul_f32_e32 v49, 0xbfb8aa3b, v54
	v_rcp_f32_e32 v54, v50
	v_mul_f32_e32 v50, 0xbfb8aa3b, v55
	v_mul_f32_e32 v52, 0xbfb8aa3b, v52
	v_exp_f32_e32 v48, v48
	v_exp_f32_e32 v49, v49
	v_exp_f32_e32 v50, v50
	v_mul_f32_e32 v51, 0xbfb8aa3b, v51
	v_pk_add_f32 v[42:43], v[42:43], v[66:67]
	v_pk_add_f32 v[40:41], v[40:41], v[64:65]
	v_exp_f32_e32 v52, v52
	v_exp_f32_e32 v51, v51
	v_mul_f32_e32 v40, 0xbfb8aa3b, v40
	v_mul_f32_e32 v41, 0xbfb8aa3b, v41
	v_mul_f32_e32 v42, 0xbfb8aa3b, v42
	v_lshl_add_u64 v[56:57], v[72:73], 0, s[86:87]
	v_exp_f32_e32 v40, v40
	v_exp_f32_e32 v41, v41
	v_exp_f32_e32 v42, v42
	v_add_f32_e32 v48, 1.0, v48
	v_add_f32_e32 v49, 1.0, v49
	v_add_f32_e32 v50, 1.0, v50
	v_add_f32_e32 v52, 1.0, v52
	v_rcp_f32_e32 v48, v48
	v_rcp_f32_e32 v49, v49
	v_rcp_f32_e32 v50, v50
	v_add_f32_e32 v51, 1.0, v51
	v_rcp_f32_e32 v52, v52
	v_rcp_f32_e32 v51, v51
	v_cvt_pk_bf16_f32 v48, v52, v48
	v_cvt_pk_bf16_f32 v49, v49, v50
	v_cvt_pk_bf16_f32 v50, v58, v53
	v_pk_add_f32 v[46:47], v[46:47], v[70:71]
	v_pk_add_f32 v[44:45], v[44:45], v[68:69]
	v_add_f32_e32 v40, 1.0, v40
	v_add_f32_e32 v41, 1.0, v41
	v_add_f32_e32 v42, 1.0, v42
	v_cvt_pk_bf16_f32 v51, v54, v51
	flat_store_dwordx2 v[56:57], v[48:49]
	flat_store_dwordx2 v[56:57], v[50:51] offset:8
	v_rcp_f32_e32 v50, v40
	v_mul_f32_e32 v40, 0xbfb8aa3b, v45
	v_rcp_f32_e32 v45, v41
	v_mul_f32_e32 v41, 0xbfb8aa3b, v46
	v_rcp_f32_e32 v46, v42
	v_mul_f32_e32 v42, 0xbfb8aa3b, v47
	v_mul_f32_e32 v44, 0xbfb8aa3b, v44
	v_exp_f32_e32 v40, v40
	v_exp_f32_e32 v41, v41
	v_exp_f32_e32 v42, v42
	v_mul_f32_e32 v43, 0xbfb8aa3b, v43
	v_pk_add_f32 v[32:33], v[32:33], v[64:65]
	v_exp_f32_e32 v44, v44
	v_exp_f32_e32 v43, v43
	v_pk_add_f32 v[34:35], v[34:35], v[66:67]
	v_mul_f32_e32 v32, 0xbfb8aa3b, v32
	v_mul_f32_e32 v33, 0xbfb8aa3b, v33
	v_lshl_add_u64 v[48:49], v[56:57], 0, s[86:87]
	v_exp_f32_e32 v32, v32
	v_exp_f32_e32 v33, v33
	v_mul_f32_e32 v34, 0xbfb8aa3b, v34
	v_exp_f32_e32 v34, v34
	v_add_f32_e32 v40, 1.0, v40
	v_add_f32_e32 v41, 1.0, v41
	v_add_f32_e32 v42, 1.0, v42
	v_add_f32_e32 v44, 1.0, v44
	v_rcp_f32_e32 v40, v40
	v_rcp_f32_e32 v41, v41
	v_rcp_f32_e32 v42, v42
	v_add_f32_e32 v43, 1.0, v43
	v_rcp_f32_e32 v44, v44
	v_rcp_f32_e32 v43, v43
	v_cvt_pk_bf16_f32 v40, v44, v40
	v_cvt_pk_bf16_f32 v41, v41, v42
	v_cvt_pk_bf16_f32 v42, v50, v45
	v_pk_add_f32 v[38:39], v[38:39], v[70:71]
	v_pk_add_f32 v[36:37], v[36:37], v[68:69]
	v_add_f32_e32 v32, 1.0, v32
	v_add_f32_e32 v33, 1.0, v33
	v_cvt_pk_bf16_f32 v43, v46, v43
	flat_store_dwordx2 v[48:49], v[40:41]
	flat_store_dwordx2 v[48:49], v[42:43] offset:8
; __device__ __forceinline__ unsigned cvt_pk_bf16(float lo, float hi) { unsigned r; asm("v_cvt_pk_bf16_f32 %0, %1, %2" : "=v"(r) : "v"(lo), "v"(hi)); return r; }
; __device__ __forceinline__ float sigmoidf_(float x) { return __builtin_amdgcn_rcpf(1.0f + __expf(-x)); }
;     __device__ __forceinline__ void operator()(f32x4 (&acc)[2][2][4][2], const GUnit& u, int wr, int wc, int fr, int fq, int tid) const {
;     ...
;             const float* bp = bgate + br * 2048 + u.pn * BM + wc * 32 + 8 * fq;
; #pragma unroll
;             for (int ai = 0; ai < 2; ++ai)
; #pragma unroll
;                 for (int bj = 0; bj < 2; ++bj) { const f32x4 b0 = *(const f32x4*)(bp + bj * HALF), b1 = *(const f32x4*)(bp + bj * HALF + 4);
; #pragma unroll
;                     for (int m = 0; m < 4; ++m) { f32x4 v0 = acc[ai][bj][m][0] + b0, v1 = acc[ai][bj][m][1] + b1;
; #pragma unroll
;                         for (int j = 0; j < 4; ++j) { v0[j] = sigmoidf_(v0[j]); v1[j] = sigmoidf_(v1[j]); }
;                         u32x4 w; w.x = cvt_pk_bf16(v0[0], v0[1]); w.y = cvt_pk_bf16(v0[2], v0[3]); w.z = cvt_pk_bf16(v1[0], v1[1]); w.w = cvt_pk_bf16(v1[2], v1[3]);
;                         st_coh16(gp, w); gp += 4096; asm volatile("" : "+v"(gp) :: "memory"); } }
	v_rcp_f32_e32 v42, v32
	v_mul_f32_e32 v32, 0xbfb8aa3b, v37
	v_rcp_f32_e32 v37, v33
	v_mul_f32_e32 v33, 0xbfb8aa3b, v38
	v_add_f32_e32 v34, 1.0, v34
	v_mul_f32_e32 v36, 0xbfb8aa3b, v36
	v_exp_f32_e32 v32, v32
	v_exp_f32_e32 v33, v33
	v_rcp_f32_e32 v38, v34
	v_mul_f32_e32 v34, 0xbfb8aa3b, v39
	v_mul_f32_e32 v35, 0xbfb8aa3b, v35
	v_exp_f32_e32 v36, v36
	v_exp_f32_e32 v34, v34
	v_exp_f32_e32 v35, v35
	v_lshl_add_u64 v[40:41], v[48:49], 0, s[86:87]
	v_add_f32_e32 v32, 1.0, v32
	v_add_f32_e32 v33, 1.0, v33
	v_add_f32_e32 v36, 1.0, v36
	v_rcp_f32_e32 v32, v32
	v_rcp_f32_e32 v33, v33
	v_add_f32_e32 v34, 1.0, v34
	v_add_f32_e32 v35, 1.0, v35
	v_rcp_f32_e32 v36, v36
	v_rcp_f32_e32 v34, v34
	v_rcp_f32_e32 v35, v35
	v_cvt_pk_bf16_f32 v32, v36, v32
	v_cvt_pk_bf16_f32 v33, v33, v34
	v_cvt_pk_bf16_f32 v34, v42, v37
	v_cvt_pk_bf16_f32 v35, v38, v35
	flat_store_dwordx2 v[40:41], v[32:33]
	flat_store_dwordx2 v[40:41], v[34:35] offset:8
	v_lshl_add_u64 v[40:41], v[40:41], 0, s[86:87]
	s_nop 1
	v_mov_b32_e32 v32, v188
	v_mov_b32_e32 v33, v189
	v_mov_b32_e32 v34, v190
	v_mov_b32_e32 v35, v191
	v_mov_b32_e32 v36, v192
	v_mov_b32_e32 v37, v193
	v_mov_b32_e32 v38, v194
	v_mov_b32_e32 v39, v195
	v_pk_add_f32 v[26:27], v[26:27], v[34:35]
	v_pk_add_f32 v[24:25], v[24:25], v[32:33]
	v_mul_f32_e32 v26, 0xbfb8aa3b, v26
	v_mul_f32_e32 v24, 0xbfb8aa3b, v24
	v_mul_f32_e32 v25, 0xbfb8aa3b, v25
	v_exp_f32_e32 v24, v24
	v_exp_f32_e32 v25, v25
	v_exp_f32_e32 v26, v26
	v_pk_add_f32 v[30:31], v[30:31], v[38:39]
	v_pk_add_f32 v[28:29], v[28:29], v[36:37]
	v_add_f32_e32 v24, 1.0, v24
	v_add_f32_e32 v25, 1.0, v25
	v_add_f32_e32 v26, 1.0, v26
	v_rcp_f32_e32 v42, v24
	v_mul_f32_e32 v24, 0xbfb8aa3b, v29
	v_rcp_f32_e32 v29, v25
	v_mul_f32_e32 v25, 0xbfb8aa3b, v30
	v_rcp_f32_e32 v30, v26
	v_mul_f32_e32 v26, 0xbfb8aa3b, v31
	v_mul_f32_e32 v28, 0xbfb8aa3b, v28
	v_exp_f32_e32 v24, v24
	v_exp_f32_e32 v25, v25
	v_exp_f32_e32 v26, v26
	v_mul_f32_e32 v27, 0xbfb8aa3b, v27
	v_pk_add_f32 v[18:19], v[18:19], v[34:35]
	v_pk_add_f32 v[16:17], v[16:17], v[32:33]
	v_exp_f32_e32 v28, v28
	v_exp_f32_e32 v27, v27
	v_mul_f32_e32 v16, 0xbfb8aa3b, v16
	v_mul_f32_e32 v17, 0xbfb8aa3b, v17
	v_mul_f32_e32 v18, 0xbfb8aa3b, v18
	v_exp_f32_e32 v16, v16
	v_exp_f32_e32 v17, v17
	v_exp_f32_e32 v18, v18
	v_add_f32_e32 v24, 1.0, v24
	v_add_f32_e32 v25, 1.0, v25
	v_add_f32_e32 v26, 1.0, v26
	v_add_f32_e32 v28, 1.0, v28
	v_rcp_f32_e32 v24, v24
	v_rcp_f32_e32 v25, v25
	v_rcp_f32_e32 v26, v26
	v_add_f32_e32 v27, 1.0, v27
	v_rcp_f32_e32 v28, v28
	v_rcp_f32_e32 v27, v27
	v_cvt_pk_bf16_f32 v24, v28, v24
	v_cvt_pk_bf16_f32 v25, v25, v26
	v_cvt_pk_bf16_f32 v26, v42, v29
	v_pk_add_f32 v[22:23], v[22:23], v[38:39]
	v_pk_add_f32 v[20:21], v[20:21], v[36:37]
	v_add_f32_e32 v16, 1.0, v16
	v_add_f32_e32 v17, 1.0, v17
	v_add_f32_e32 v18, 1.0, v18
	v_cvt_pk_bf16_f32 v27, v30, v27
	flat_store_dwordx2 v[40:41], v[24:25]
	flat_store_dwordx2 v[40:41], v[26:27] offset:8
	v_rcp_f32_e32 v26, v16
	v_mul_f32_e32 v16, 0xbfb8aa3b, v21
	v_rcp_f32_e32 v21, v17
	v_mul_f32_e32 v17, 0xbfb8aa3b, v22
	v_rcp_f32_e32 v22, v18
	v_mul_f32_e32 v18, 0xbfb8aa3b, v23
	v_mul_f32_e32 v20, 0xbfb8aa3b, v20
	v_exp_f32_e32 v16, v16
	v_exp_f32_e32 v17, v17
	v_exp_f32_e32 v18, v18
	v_mul_f32_e32 v19, 0xbfb8aa3b, v19
	v_pk_add_f32 v[10:11], v[10:11], v[34:35]
	v_pk_add_f32 v[8:9], v[8:9], v[32:33]
	v_exp_f32_e32 v20, v20
	v_exp_f32_e32 v19, v19
	v_mul_f32_e32 v8, 0xbfb8aa3b, v8
	v_mul_f32_e32 v9, 0xbfb8aa3b, v9
	v_mul_f32_e32 v10, 0xbfb8aa3b, v10
	v_lshl_add_u64 v[24:25], v[40:41], 0, s[86:87]
	v_exp_f32_e32 v8, v8
	v_exp_f32_e32 v9, v9
	v_exp_f32_e32 v10, v10
	v_add_f32_e32 v16, 1.0, v16
	v_add_f32_e32 v17, 1.0, v17
	v_add_f32_e32 v18, 1.0, v18
	v_add_f32_e32 v20, 1.0, v20
	v_rcp_f32_e32 v16, v16
	v_rcp_f32_e32 v17, v17
	v_rcp_f32_e32 v18, v18
	v_add_f32_e32 v19, 1.0, v19
	v_rcp_f32_e32 v20, v20
	v_rcp_f32_e32 v19, v19
	v_cvt_pk_bf16_f32 v16, v20, v16
	v_cvt_pk_bf16_f32 v17, v17, v18
	v_cvt_pk_bf16_f32 v18, v26, v21
	v_pk_add_f32 v[14:15], v[14:15], v[38:39]
	v_pk_add_f32 v[12:13], v[12:13], v[36:37]
	v_add_f32_e32 v8, 1.0, v8
	v_add_f32_e32 v9, 1.0, v9
	v_add_f32_e32 v10, 1.0, v10
	v_cvt_pk_bf16_f32 v19, v22, v19
	flat_store_dwordx2 v[24:25], v[16:17]
	flat_store_dwordx2 v[24:25], v[18:19] offset:8
	v_rcp_f32_e32 v18, v8
	v_mul_f32_e32 v8, 0xbfb8aa3b, v13
	v_rcp_f32_e32 v13, v9
	v_mul_f32_e32 v9, 0xbfb8aa3b, v14
	v_rcp_f32_e32 v14, v10
	v_mul_f32_e32 v10, 0xbfb8aa3b, v15
	v_mul_f32_e32 v12, 0xbfb8aa3b, v12
	v_exp_f32_e32 v8, v8
	v_exp_f32_e32 v9, v9
	v_exp_f32_e32 v10, v10
	v_mul_f32_e32 v11, 0xbfb8aa3b, v11
	v_pk_add_f32 v[0:1], v[0:1], v[32:33]
	v_exp_f32_e32 v12, v12
	v_exp_f32_e32 v11, v11
	v_pk_add_f32 v[2:3], v[2:3], v[34:35]
	v_mul_f32_e32 v0, 0xbfb8aa3b, v0
	v_mul_f32_e32 v1, 0xbfb8aa3b, v1
	v_lshl_add_u64 v[16:17], v[24:25], 0, s[86:87]
	v_exp_f32_e32 v0, v0
	v_exp_f32_e32 v1, v1
	v_mul_f32_e32 v2, 0xbfb8aa3b, v2
	v_exp_f32_e32 v2, v2
	v_add_f32_e32 v8, 1.0, v8
	v_add_f32_e32 v9, 1.0, v9
	v_add_f32_e32 v10, 1.0, v10
	v_add_f32_e32 v12, 1.0, v12
	v_rcp_f32_e32 v8, v8
	v_rcp_f32_e32 v9, v9
	v_rcp_f32_e32 v10, v10
	v_add_f32_e32 v11, 1.0, v11
	v_rcp_f32_e32 v12, v12
	v_rcp_f32_e32 v11, v11
	v_cvt_pk_bf16_f32 v8, v12, v8
	v_cvt_pk_bf16_f32 v9, v9, v10
	v_cvt_pk_bf16_f32 v10, v18, v13
	v_pk_add_f32 v[6:7], v[6:7], v[38:39]
	v_pk_add_f32 v[4:5], v[4:5], v[36:37]
	v_add_f32_e32 v0, 1.0, v0
	v_add_f32_e32 v1, 1.0, v1
	v_cvt_pk_bf16_f32 v11, v14, v11
	flat_store_dwordx2 v[16:17], v[8:9]
	flat_store_dwordx2 v[16:17], v[10:11] offset:8
	v_rcp_f32_e32 v10, v0
	v_mul_f32_e32 v0, 0xbfb8aa3b, v5
	v_rcp_f32_e32 v5, v1
	v_mul_f32_e32 v1, 0xbfb8aa3b, v6
	v_add_f32_e32 v2, 1.0, v2
	v_mul_f32_e32 v4, 0xbfb8aa3b, v4
	v_exp_f32_e32 v0, v0
	v_exp_f32_e32 v1, v1
	v_rcp_f32_e32 v6, v2
	v_mul_f32_e32 v2, 0xbfb8aa3b, v7
	v_mul_f32_e32 v3, 0xbfb8aa3b, v3
	v_exp_f32_e32 v4, v4
	v_exp_f32_e32 v2, v2
	v_exp_f32_e32 v3, v3
	v_lshl_add_u64 v[8:9], v[16:17], 0, s[86:87]
	v_add_f32_e32 v0, 1.0, v0
	v_add_f32_e32 v1, 1.0, v1
	v_add_f32_e32 v4, 1.0, v4
	v_rcp_f32_e32 v0, v0
	v_rcp_f32_e32 v1, v1
	v_add_f32_e32 v2, 1.0, v2
	v_add_f32_e32 v3, 1.0, v3
	v_rcp_f32_e32 v4, v4
	v_rcp_f32_e32 v2, v2
	v_rcp_f32_e32 v3, v3
	v_cvt_pk_bf16_f32 v0, v4, v0
	v_cvt_pk_bf16_f32 v1, v1, v2
	v_cvt_pk_bf16_f32 v2, v10, v5
	v_cvt_pk_bf16_f32 v3, v6, v3
	flat_store_dwordx2 v[8:9], v[0:1]
	flat_store_dwordx2 v[8:9], v[2:3] offset:8
	v_lshl_add_u64 v[0:1], v[8:9], 0, s[86:87]
	s_branch .LBB0_562
